# write-through only on the weight-conversion dwordx4 stores (GEMM epilogue stores left write-back)
# speedup vs baseline: 1.0001x; 1.0001x over previous
; #define LAS __attribute__((address_space(3)))
; __device__ __forceinline__ unsigned cvtpk(float lo, float hi) { f32x2 v = {lo, hi}; bf16x2_t b = __builtin_convertvector(v, bf16x2_t); return __builtin_bit_cast(unsigned, b); }
; __device__ __forceinline__ void witem_store(const WItem& w, int K, bf16_t* WT, int kvperm, LAS float* scr, int item, int nblk, int lane) {
;     ...
;     for (int i = 0; i < 8; ++i) { LAS float* d = scr + (8 * i + rr) * 33 + col; const float g = w.g[i]; d[0] = w.v[i].x * g; d[1] = w.v[i].y * g; d[2] = w.v[i].z * g; d[3] = w.v[i].w * g; }
;     asm volatile("s_waitcnt lgkmcnt(0)" ::: "memory");
;     const int c = lane & 7;
; #pragma unroll
;     for (int j = 0; j < 4; ++j) { const int n = (lane >> 3) + 8 * j; const LAS float* s = scr + (8 * c) * 33 + n;
;         u32x4 o; o.x = cvtpk(s[0 * 33], s[1 * 33]); o.y = cvtpk(s[2 * 33], s[3 * 33]); o.z = cvtpk(s[4 * 33], s[5 * 33]); o.w = cvtpk(s[6 * 33], s[7 * 33]);
;         int nr = n0 + n; if (kvperm == 1) { const int hh = nr >> 8, ww = nr & 255; nr = (ww < 128) ? hh * 128 + ww : 2048 + hh * 128 + (ww - 128); }
;         else if (kvperm == 2) { const int isv = nr >= 5632, f = isv ? nr - 5632 : nr; nr = (f >> 7) * 256 + isv * 128 + (f & 127); }
;         *(u32x4*)(WT + (size_t)nr * K + k0 + 8 * c) = o; }
;     ...
;     while (it < i1) {
;         cur = nxt;
;         const int nit = it + NGW;
;         if (nit < i1) witem_load(nxt, W, N, gk, nit, nblk, lane);
;         witem_store(cur, K, WT, kvperm, scr, it, nblk, lane);
;         it = nit;
;     }
.LBB0_382:
	v_pk_mul_f32 v[2:3], v[2:3], v[72:73] op_sel_hi:[1,0]
	ds_write2_b32 v79, v2, v3 offset1:1
	v_pk_mul_f32 v[2:3], v[4:5], v[72:73] op_sel_hi:[1,0]
	ds_write2_b32 v79, v2, v3 offset0:2 offset1:3
	v_pk_mul_f32 v[2:3], v[6:7], v[74:75] op_sel_hi:[1,0]
	v_add_u32_e32 v4, 0x420, v79
	ds_write2_b32 v4, v2, v3 offset1:1
	v_pk_mul_f32 v[2:3], v[8:9], v[74:75] op_sel_hi:[1,0]
	v_add_u32_e32 v4, 0x428, v79
	ds_write2_b32 v4, v2, v3 offset1:1
	v_pk_mul_f32 v[2:3], v[10:11], v[76:77] op_sel_hi:[1,0]
	v_add_u32_e32 v4, 0x840, v79
	ds_write2_b32 v4, v2, v3 offset1:1
	v_pk_mul_f32 v[2:3], v[12:13], v[76:77] op_sel_hi:[1,0]
	v_add_u32_e32 v4, 0x848, v79
	ds_write2_b32 v4, v2, v3 offset1:1
	v_pk_mul_f32 v[2:3], v[14:15], v[78:79] op_sel_hi:[1,0]
	v_add_u32_e32 v4, 0xc60, v79
	ds_write2_b32 v4, v2, v3 offset1:1
	v_pk_mul_f32 v[2:3], v[16:17], v[78:79] op_sel_hi:[1,0]
	v_add_u32_e32 v4, 0xc68, v79
	ds_write2_b32 v4, v2, v3 offset1:1
	v_pk_mul_f32 v[2:3], v[18:19], v[84:85] op_sel_hi:[1,0]
	v_add_u32_e32 v4, 0x1080, v79
	ds_write2_b32 v4, v2, v3 offset1:1
	v_pk_mul_f32 v[2:3], v[20:21], v[84:85] op_sel_hi:[1,0]
	v_add_u32_e32 v4, 0x1088, v79
	ds_write2_b32 v4, v2, v3 offset1:1
	v_pk_mul_f32 v[2:3], v[26:27], v[86:87] op_sel_hi:[1,0]
	v_add_u32_e32 v4, 0x14a0, v79
	s_mul_hi_i32 s4, s26, 0x2e8ba2e9
	ds_write2_b32 v4, v2, v3 offset1:1
	v_pk_mul_f32 v[2:3], v[28:29], v[86:87] op_sel_hi:[1,0]
	v_add_u32_e32 v4, 0x14a8, v79
	s_lshr_b32 s5, s4, 31
	s_ashr_i32 s4, s4, 6
	ds_write2_b32 v4, v2, v3 offset1:1
	v_pk_mul_f32 v[2:3], v[30:31], v[88:89] op_sel_hi:[1,0]
	v_add_u32_e32 v4, 0x18c0, v79
	s_add_i32 s6, s4, s5
	ds_write2_b32 v4, v2, v3 offset1:1
	v_pk_mul_f32 v[2:3], v[32:33], v[88:89] op_sel_hi:[1,0]
	v_add_u32_e32 v4, 0x18c8, v79
	s_lshl_b32 s4, s6, 6
	ds_write2_b32 v4, v2, v3 offset1:1
	s_waitcnt vmcnt(0)
	v_pk_mul_f32 v[2:3], v[38:39], v[90:91] op_sel_hi:[1,0]
	v_add_u32_e32 v4, 0x1ce0, v79
	ds_write2_b32 v4, v2, v3 offset1:1
	v_pk_mul_f32 v[2:3], v[40:41], v[90:91] op_sel_hi:[1,0]
	v_add_u32_e32 v4, 0x1ce8, v79
	s_ashr_i32 s5, s4, 31
	ds_write2_b32 v4, v2, v3 offset1:1
	v_lshl_add_u64 v[24:25], s[4:5], 1, v[82:83]
	s_mul_i32 s4, s6, 0xffffd400
	s_waitcnt lgkmcnt(0)
	s_add_i32 s4, s4, s28
	ds_read2_b32 v[6:7], v77 offset0:33 offset1:41
	ds_read2_b32 v[8:9], v77 offset1:8
	ds_read2_b32 v[10:11], v77 offset0:66 offset1:74
	ds_read2_b32 v[12:13], v77 offset0:99 offset1:107
	ds_read2_b32 v[14:15], v77 offset0:132 offset1:140
	ds_read2_b32 v[16:17], v77 offset0:165 offset1:173
	ds_read2_b32 v[18:19], v77 offset0:198 offset1:206
	ds_read2_b32 v[20:21], v77 offset0:231 offset1:239
	v_add_u32_e32 v28, s4, v87
	s_waitcnt lgkmcnt(6)
	v_cvt_pk_bf16_f32 v2, v8, v6
	v_add_u32_e32 v6, 0xffffea00, v28
	v_cmp_lt_i32_e32 vcc, s34, v28
	s_waitcnt lgkmcnt(4)
	v_cvt_pk_bf16_f32 v3, v10, v12
	s_waitcnt lgkmcnt(2)
	v_cvt_pk_bf16_f32 v4, v14, v16
	v_cndmask_b32_e32 v6, v28, v6, vcc
	v_lshlrev_b32_e32 v8, 1, v6
	v_and_b32_e32 v8, 0xffffff00, v8
	v_cndmask_b32_e32 v10, 0, v85, vcc
	v_and_b32_e32 v6, 0x67, v6
	v_or3_b32 v26, v6, v10, v8
	v_ashrrev_i32_e32 v27, 31, v26
	v_lshlrev_b64 v[26:27], 12, v[26:27]
	s_waitcnt lgkmcnt(0)
	v_cvt_pk_bf16_f32 v5, v18, v20
	v_lshl_add_u64 v[26:27], v[24:25], 0, v[26:27]
	v_add_u32_e32 v6, 8, v28
	global_store_dwordx4 v[26:27], v[2:5], off sc0 sc1
	v_cmp_lt_i32_e32 vcc, s34, v6
	v_mov_b64_e32 v[30:31], v[62:63]
	v_cvt_pk_bf16_f32 v2, v9, v7
	v_add_u32_e32 v7, 0xffffea08, v28
	v_cndmask_b32_e32 v6, v6, v7, vcc
	v_lshlrev_b32_e32 v7, 1, v6
	v_and_b32_e32 v7, 0xffffff00, v7
	v_cndmask_b32_e32 v8, 0, v85, vcc
	v_and_b32_e32 v6, 0x6f, v6
	v_or3_b32 v6, v6, v8, v7
	v_ashrrev_i32_e32 v7, 31, v6
	v_lshlrev_b64 v[6:7], 12, v[6:7]
	v_cvt_pk_bf16_f32 v3, v11, v13
	v_cvt_pk_bf16_f32 v4, v15, v17
	v_cvt_pk_bf16_f32 v5, v19, v21
	v_lshl_add_u64 v[6:7], v[24:25], 0, v[6:7]
	ds_read2_b32 v[8:9], v77 offset0:16 offset1:24
	ds_read2_b32 v[10:11], v77 offset0:49 offset1:57
	ds_read2_b32 v[12:13], v77 offset0:82 offset1:90
	ds_read2_b32 v[14:15], v77 offset0:115 offset1:123
	ds_read2_b32 v[16:17], v77 offset0:148 offset1:156
	ds_read2_b32 v[18:19], v77 offset0:181 offset1:189
	ds_read2_b32 v[20:21], v77 offset0:214 offset1:222
	ds_read2_b32 v[26:27], v77 offset0:247 offset1:255
	global_store_dwordx4 v[6:7], v[2:5], off sc0 sc1
	v_add_u32_e32 v6, 16, v28
	v_add_u32_e32 v7, 0xffffea10, v28
	v_cmp_lt_i32_e32 vcc, s34, v6
	s_waitcnt lgkmcnt(6)
	v_cvt_pk_bf16_f32 v2, v8, v10
	s_waitcnt lgkmcnt(4)
	v_cvt_pk_bf16_f32 v3, v12, v14
	v_cndmask_b32_e32 v6, v6, v7, vcc
	v_lshlrev_b32_e32 v7, 1, v6
	v_and_b32_e32 v7, 0xffffff00, v7
	v_cndmask_b32_e32 v8, 0, v85, vcc
	v_and_b32_e32 v6, 0x77, v6
	v_or3_b32 v6, v6, v8, v7
	v_ashrrev_i32_e32 v7, 31, v6
	v_lshlrev_b64 v[6:7], 12, v[6:7]
	s_waitcnt lgkmcnt(2)
	v_cvt_pk_bf16_f32 v4, v16, v18
	s_waitcnt lgkmcnt(0)
	v_cvt_pk_bf16_f32 v5, v20, v26
	v_lshl_add_u64 v[6:7], v[24:25], 0, v[6:7]
	global_store_dwordx4 v[6:7], v[2:5], off sc0 sc1
	v_mov_b64_e32 v[38:39], v[66:67]
	v_add_u32_e32 v87, s29, v87
	v_add_u32_e32 v2, 24, v28
	v_add_u32_e32 v3, 0xffffea18, v28
	v_cmp_lt_i32_e32 vcc, s34, v2
	v_cvt_pk_bf16_f32 v5, v21, v27
	v_mov_b64_e32 v[26:27], v[58:59]
	v_cndmask_b32_e32 v2, v2, v3, vcc
	v_lshlrev_b32_e32 v3, 1, v2
	v_and_b32_e32 v3, 0xffffff00, v3
	v_cndmask_b32_e32 v4, 0, v85, vcc
	v_and_b32_e32 v2, 0x7f, v2
	v_or3_b32 v6, v2, v4, v3
	v_ashrrev_i32_e32 v7, 31, v6
	v_lshlrev_b64 v[6:7], 12, v[6:7]
	v_cvt_pk_bf16_f32 v2, v9, v11
	v_cvt_pk_bf16_f32 v3, v13, v15
	v_cvt_pk_bf16_f32 v4, v17, v19
	v_lshl_add_u64 v[6:7], v[24:25], 0, v[6:7]
	global_store_dwordx4 v[6:7], v[2:5], off
	s_waitcnt lgkmcnt(0)
	v_mov_b64_e32 v[6:7], v[42:43]
	v_mov_b64_e32 v[10:11], v[46:47]
	v_mov_b64_e32 v[2:3], v[34:35]
	v_mov_b64_e32 v[14:15], v[50:51]
	v_mov_b64_e32 v[18:19], v[54:55]
	s_add_i32 s35, s35, s29
	v_add_u32_e32 v73, s29, v73
	s_andn2_b64 vcc, exec, s[18:19]
	s_mov_b32 s26, s36
	v_mov_b64_e32 v[4:5], v[36:37]
	v_mov_b64_e32 v[8:9], v[44:45]
	v_mov_b64_e32 v[12:13], v[48:49]
	v_mov_b64_e32 v[16:17], v[52:53]
	v_mov_b64_e32 v[20:21], v[56:57]
	v_mov_b64_e32 v[28:29], v[60:61]
	v_mov_b64_e32 v[32:33], v[64:65]
	v_mov_b64_e32 v[40:41], v[68:69]
	v_mov_b32_e32 v72, v91
	v_mov_b32_e32 v74, v96
	v_mov_b32_e32 v76, v97
	v_mov_b32_e32 v78, v98
	v_mov_b32_e32 v84, v99
	v_mov_b32_e32 v86, v100
	v_mov_b32_e32 v88, v101
	v_mov_b32_e32 v90, v23
	s_cbranch_vccz .LBB0_422

; #define LAS __attribute__((address_space(3)))
; __device__ __forceinline__ unsigned cvtpk(float lo, float hi) { f32x2 v = {lo, hi}; bf16x2_t b = __builtin_convertvector(v, bf16x2_t); return __builtin_bit_cast(unsigned, b); }
; __device__ __forceinline__ void witem_store(const WItem& w, int K, bf16_t* WT, int kvperm, LAS float* scr, int item, int nblk, int lane) {
;     ...
;     for (int i = 0; i < 8; ++i) { LAS float* d = scr + (8 * i + rr) * 33 + col; const float g = w.g[i]; d[0] = w.v[i].x * g; d[1] = w.v[i].y * g; d[2] = w.v[i].z * g; d[3] = w.v[i].w * g; }
;     asm volatile("s_waitcnt lgkmcnt(0)" ::: "memory");
;     const int c = lane & 7;
; #pragma unroll
;     for (int j = 0; j < 4; ++j) { const int n = (lane >> 3) + 8 * j; const LAS float* s = scr + (8 * c) * 33 + n;
;         u32x4 o; o.x = cvtpk(s[0 * 33], s[1 * 33]); o.y = cvtpk(s[2 * 33], s[3 * 33]); o.z = cvtpk(s[4 * 33], s[5 * 33]); o.w = cvtpk(s[6 * 33], s[7 * 33]);
;         int nr = n0 + n; if (kvperm == 1) { const int hh = nr >> 8, ww = nr & 255; nr = (ww < 128) ? hh * 128 + ww : 2048 + hh * 128 + (ww - 128); }
;         else if (kvperm == 2) { const int isv = nr >= 5632, f = isv ? nr - 5632 : nr; nr = (f >> 7) * 256 + isv * 128 + (f & 127); }
;         *(u32x4*)(WT + (size_t)nr * K + k0 + 8 * c) = o; }
;     ...
;     while (it < i1) {
;         cur = nxt;
;         const int nit = it + NGW;
;         if (nit < i1) witem_load(nxt, W, N, gk, nit, nblk, lane);
;         witem_store(cur, K, WT, kvperm, scr, it, nblk, lane);
;         it = nit;
;     }
.LBB0_515:
	v_pk_mul_f32 v[4:5], v[18:19], v[76:77] op_sel_hi:[1,0]
	ds_write2_b32 v81, v4, v5 offset1:1
	v_pk_mul_f32 v[4:5], v[20:21], v[76:77] op_sel_hi:[1,0]
	ds_write2_b32 v81, v4, v5 offset0:2 offset1:3
	v_pk_mul_f32 v[4:5], v[6:7], v[78:79] op_sel_hi:[1,0]
	v_add_u32_e32 v6, 0x420, v81
	ds_write2_b32 v6, v4, v5 offset1:1
	v_pk_mul_f32 v[4:5], v[8:9], v[78:79] op_sel_hi:[1,0]
	v_add_u32_e32 v6, 0x428, v81
	ds_write2_b32 v6, v4, v5 offset1:1
	v_pk_mul_f32 v[4:5], v[26:27], v[80:81] op_sel_hi:[1,0]
	v_add_u32_e32 v6, 0x840, v81
	ds_write2_b32 v6, v4, v5 offset1:1
	v_pk_mul_f32 v[4:5], v[28:29], v[80:81] op_sel_hi:[1,0]
	v_add_u32_e32 v6, 0x848, v81
	ds_write2_b32 v6, v4, v5 offset1:1
	v_pk_mul_f32 v[4:5], v[22:23], v[82:83] op_sel_hi:[1,0]
	v_add_u32_e32 v6, 0xc60, v81
	ds_write2_b32 v6, v4, v5 offset1:1
	v_pk_mul_f32 v[4:5], v[24:25], v[82:83] op_sel_hi:[1,0]
	v_add_u32_e32 v6, 0xc68, v81
	ds_write2_b32 v6, v4, v5 offset1:1
	v_pk_mul_f32 v[4:5], v[42:43], v[84:85] op_sel_hi:[1,0]
	v_add_u32_e32 v6, 0x1080, v81
	ds_write2_b32 v6, v4, v5 offset1:1
	v_pk_mul_f32 v[4:5], v[44:45], v[84:85] op_sel_hi:[1,0]
	v_add_u32_e32 v6, 0x1088, v81
	ds_write2_b32 v6, v4, v5 offset1:1
	s_waitcnt vmcnt(7)
	v_pk_mul_f32 v[4:5], v[34:35], v[86:87] op_sel_hi:[1,0]
	v_add_u32_e32 v6, 0x14a0, v81
	s_mul_hi_i32 s12, s19, 0x2e8ba2e9
	ds_write2_b32 v6, v4, v5 offset1:1
	v_pk_mul_f32 v[4:5], v[36:37], v[86:87] op_sel_hi:[1,0]
	v_add_u32_e32 v6, 0x14a8, v81
	s_lshr_b32 s13, s12, 31
	s_ashr_i32 s12, s12, 6
	ds_write2_b32 v6, v4, v5 offset1:1
	s_waitcnt vmcnt(6)
	v_pk_mul_f32 v[4:5], v[54:55], v[88:89] op_sel_hi:[1,0]
	v_add_u32_e32 v6, 0x18c0, v81
	s_add_i32 s19, s12, s13
	ds_write2_b32 v6, v4, v5 offset1:1
	v_pk_mul_f32 v[4:5], v[56:57], v[88:89] op_sel_hi:[1,0]
	v_add_u32_e32 v6, 0x18c8, v81
	s_lshl_b32 s12, s19, 6
	ds_write2_b32 v6, v4, v5 offset1:1
	s_waitcnt vmcnt(5)
	v_pk_mul_f32 v[4:5], v[46:47], v[90:91] op_sel_hi:[1,0]
	v_add_u32_e32 v6, 0x1ce0, v81
	ds_write2_b32 v6, v4, v5 offset1:1
	v_pk_mul_f32 v[4:5], v[48:49], v[90:91] op_sel_hi:[1,0]
	v_add_u32_e32 v6, 0x1ce8, v81
	s_ashr_i32 s13, s12, 31
	ds_write2_b32 v6, v4, v5 offset1:1
	v_lshl_add_u64 v[36:37], s[12:13], 1, v[74:75]
	s_mul_i32 s12, s19, 0xffffd400
	s_waitcnt lgkmcnt(0)
	s_add_i32 s12, s12, s2
	ds_read2_b32 v[8:9], v79 offset0:33 offset1:41
	ds_read2_b32 v[18:19], v79 offset1:8
	ds_read2_b32 v[20:21], v79 offset0:66 offset1:74
	ds_read2_b32 v[22:23], v79 offset0:99 offset1:107
	ds_read2_b32 v[24:25], v79 offset0:132 offset1:140
	ds_read2_b32 v[26:27], v79 offset0:165 offset1:173
	ds_read2_b32 v[28:29], v79 offset0:198 offset1:206
	ds_read2_b32 v[34:35], v79 offset0:231 offset1:239
	v_add_u32_e32 v44, s12, v85
	s_waitcnt lgkmcnt(6)
	v_cvt_pk_bf16_f32 v4, v18, v8
	v_add_u32_e32 v8, 0xffffea00, v44
	v_cmp_lt_i32_e32 vcc, s18, v44
	s_waitcnt lgkmcnt(4)
	v_cvt_pk_bf16_f32 v5, v20, v22
	s_waitcnt lgkmcnt(2)
	v_cvt_pk_bf16_f32 v6, v24, v26
	v_cndmask_b32_e32 v8, v44, v8, vcc
	v_lshlrev_b32_e32 v18, 1, v8
	v_and_b32_e32 v18, 0xffffff00, v18
	v_cndmask_b32_e32 v20, 0, v83, vcc
	v_and_b32_e32 v8, 0x67, v8
	v_or3_b32 v42, v8, v20, v18
	v_ashrrev_i32_e32 v43, 31, v42
	v_lshlrev_b64 v[42:43], 12, v[42:43]
	s_waitcnt lgkmcnt(0)
	v_cvt_pk_bf16_f32 v7, v28, v34
	v_lshl_add_u64 v[42:43], v[36:37], 0, v[42:43]
	v_add_u32_e32 v8, 8, v44
	global_store_dwordx4 v[42:43], v[4:7], off sc0 sc1
	v_cmp_lt_i32_e32 vcc, s18, v8
	s_waitcnt vmcnt(3)
	v_mov_b64_e32 v[54:55], v[62:63]
	v_cvt_pk_bf16_f32 v4, v19, v9
	v_add_u32_e32 v9, 0xffffea08, v44
	v_cndmask_b32_e32 v8, v8, v9, vcc
	v_lshlrev_b32_e32 v9, 1, v8
	v_and_b32_e32 v9, 0xffffff00, v9
	v_cndmask_b32_e32 v18, 0, v83, vcc
	v_and_b32_e32 v8, 0x6f, v8
	v_or3_b32 v8, v8, v18, v9
	v_ashrrev_i32_e32 v9, 31, v8
	v_lshlrev_b64 v[8:9], 12, v[8:9]
	v_cvt_pk_bf16_f32 v5, v21, v23
	v_cvt_pk_bf16_f32 v6, v25, v27
	v_cvt_pk_bf16_f32 v7, v29, v35
	v_lshl_add_u64 v[8:9], v[36:37], 0, v[8:9]
	ds_read2_b32 v[18:19], v79 offset0:16 offset1:24
	ds_read2_b32 v[20:21], v79 offset0:49 offset1:57
	ds_read2_b32 v[22:23], v79 offset0:82 offset1:90
	ds_read2_b32 v[24:25], v79 offset0:115 offset1:123
	ds_read2_b32 v[26:27], v79 offset0:148 offset1:156
	ds_read2_b32 v[28:29], v79 offset0:181 offset1:189
	ds_read2_b32 v[34:35], v79 offset0:214 offset1:222
	ds_read2_b32 v[42:43], v79 offset0:247 offset1:255
	global_store_dwordx4 v[8:9], v[4:7], off sc0 sc1
	v_add_u32_e32 v8, 16, v44
	v_add_u32_e32 v9, 0xffffea10, v44
	v_cmp_lt_i32_e32 vcc, s18, v8
	s_waitcnt lgkmcnt(6)
	v_cvt_pk_bf16_f32 v4, v18, v20
	s_waitcnt lgkmcnt(4)
	v_cvt_pk_bf16_f32 v5, v22, v24
	v_cndmask_b32_e32 v8, v8, v9, vcc
	v_lshlrev_b32_e32 v9, 1, v8
	v_and_b32_e32 v9, 0xffffff00, v9
	v_cndmask_b32_e32 v18, 0, v83, vcc
	v_and_b32_e32 v8, 0x77, v8
	v_or3_b32 v8, v8, v18, v9
	v_ashrrev_i32_e32 v9, 31, v8
	v_lshlrev_b64 v[8:9], 12, v[8:9]
	s_waitcnt lgkmcnt(2)
	v_cvt_pk_bf16_f32 v6, v26, v28
	s_waitcnt lgkmcnt(0)
	v_cvt_pk_bf16_f32 v7, v34, v42
	v_lshl_add_u64 v[8:9], v[36:37], 0, v[8:9]
	global_store_dwordx4 v[8:9], v[4:7], off sc0 sc1
	s_waitcnt vmcnt(4)
	v_mov_b64_e32 v[46:47], v[66:67]
	v_add_u32_e32 v85, s14, v85
	v_add_u32_e32 v4, 24, v44
	v_add_u32_e32 v5, 0xffffea18, v44
	v_cmp_lt_i32_e32 vcc, s18, v4
	v_cvt_pk_bf16_f32 v7, v35, v43
	v_mov_b64_e32 v[42:43], v[50:51]
	v_cndmask_b32_e32 v4, v4, v5, vcc
	v_lshlrev_b32_e32 v5, 1, v4
	v_and_b32_e32 v5, 0xffffff00, v5
	v_cndmask_b32_e32 v6, 0, v83, vcc
	v_and_b32_e32 v4, 0x7f, v4
	v_or3_b32 v8, v4, v6, v5
	v_ashrrev_i32_e32 v9, 31, v8
	v_lshlrev_b64 v[8:9], 12, v[8:9]
	v_cvt_pk_bf16_f32 v4, v19, v21
	v_cvt_pk_bf16_f32 v5, v23, v25
	v_cvt_pk_bf16_f32 v6, v27, v29
	v_lshl_add_u64 v[8:9], v[36:37], 0, v[8:9]
	global_store_dwordx4 v[8:9], v[4:7], off
	s_waitcnt lgkmcnt(0)
	v_mov_b64_e32 v[20:21], v[16:17]
	v_mov_b64_e32 v[26:27], v[30:31]
	v_mov_b64_e32 v[6:7], v[10:11]
	v_mov_b64_e32 v[22:23], v[38:39]
	v_mov_b64_e32 v[34:35], v[58:59]
	s_add_i32 s20, s20, s14
	v_add_u32_e32 v77, s14, v77
	s_andn2_b64 vcc, exec, s[6:7]
	s_mov_b32 s19, s21
	v_mov_b64_e32 v[18:19], v[14:15]
	v_mov_b64_e32 v[8:9], v[12:13]
	v_mov_b64_e32 v[28:29], v[32:33]
	v_mov_b64_e32 v[24:25], v[40:41]
	v_mov_b64_e32 v[44:45], v[52:53]
	v_mov_b64_e32 v[36:37], v[60:61]
	v_mov_b64_e32 v[56:57], v[64:65]
	v_mov_b64_e32 v[48:49], v[68:69]
	v_mov_b32_e32 v76, v87
	v_mov_b32_e32 v78, v89
	v_mov_b32_e32 v80, v91
	v_mov_b32_e32 v82, v93
	v_mov_b32_e32 v84, v98
	v_mov_b32_e32 v86, v99
	v_mov_b32_e32 v88, v100
	s_waitcnt vmcnt(4)
	v_mov_b32_e32 v90, v3
	s_cbranch_vccz .LBB0_533

; #define LAS __attribute__((address_space(3)))
; __device__ __forceinline__ unsigned cvtpk(float lo, float hi) { f32x2 v = {lo, hi}; bf16x2_t b = __builtin_convertvector(v, bf16x2_t); return __builtin_bit_cast(unsigned, b); }
; __device__ __forceinline__ void witem_store(const WItem& w, int K, bf16_t* WT, int kvperm, LAS float* scr, int item, int nblk, int lane) {
;     ...
;     for (int i = 0; i < 8; ++i) { LAS float* d = scr + (8 * i + rr) * 33 + col; const float g = w.g[i]; d[0] = w.v[i].x * g; d[1] = w.v[i].y * g; d[2] = w.v[i].z * g; d[3] = w.v[i].w * g; }
;     asm volatile("s_waitcnt lgkmcnt(0)" ::: "memory");
;     const int c = lane & 7;
; #pragma unroll
;     for (int j = 0; j < 4; ++j) { const int n = (lane >> 3) + 8 * j; const LAS float* s = scr + (8 * c) * 33 + n;
;         u32x4 o; o.x = cvtpk(s[0 * 33], s[1 * 33]); o.y = cvtpk(s[2 * 33], s[3 * 33]); o.z = cvtpk(s[4 * 33], s[5 * 33]); o.w = cvtpk(s[6 * 33], s[7 * 33]);
;         int nr = n0 + n; if (kvperm == 1) { const int hh = nr >> 8, ww = nr & 255; nr = (ww < 128) ? hh * 128 + ww : 2048 + hh * 128 + (ww - 128); }
;         else if (kvperm == 2) { const int isv = nr >= 5632, f = isv ? nr - 5632 : nr; nr = (f >> 7) * 256 + isv * 128 + (f & 127); }
;         *(u32x4*)(WT + (size_t)nr * K + k0 + 8 * c) = o; }
;     ...
;     while (it < i1) {
;         cur = nxt;
;         const int nit = it + NGW;
;         if (nit < i1) witem_load(nxt, W, N, gk, nit, nblk, lane);
;         witem_store(cur, K, WT, kvperm, scr, it, nblk, lane);
;         it = nit;
;     }
.LBB0_737:
	v_pk_mul_f32 v[2:3], v[16:17], v[72:73] op_sel_hi:[1,0]
	ds_write2_b32 v79, v2, v3 offset1:1
	v_pk_mul_f32 v[2:3], v[18:19], v[72:73] op_sel_hi:[1,0]
	ds_write2_b32 v79, v2, v3 offset0:2 offset1:3
	v_pk_mul_f32 v[2:3], v[4:5], v[74:75] op_sel_hi:[1,0]
	v_add_u32_e32 v4, 0x420, v79
	ds_write2_b32 v4, v2, v3 offset1:1
	v_pk_mul_f32 v[2:3], v[6:7], v[74:75] op_sel_hi:[1,0]
	v_add_u32_e32 v4, 0x428, v79
	ds_write2_b32 v4, v2, v3 offset1:1
	v_pk_mul_f32 v[2:3], v[24:25], v[76:77] op_sel_hi:[1,0]
	v_add_u32_e32 v4, 0x840, v79
	ds_write2_b32 v4, v2, v3 offset1:1
	v_pk_mul_f32 v[2:3], v[26:27], v[76:77] op_sel_hi:[1,0]
	v_add_u32_e32 v4, 0x848, v79
	ds_write2_b32 v4, v2, v3 offset1:1
	v_pk_mul_f32 v[2:3], v[20:21], v[78:79] op_sel_hi:[1,0]
	v_add_u32_e32 v4, 0xc60, v79
	ds_write2_b32 v4, v2, v3 offset1:1
	v_pk_mul_f32 v[2:3], v[22:23], v[78:79] op_sel_hi:[1,0]
	v_add_u32_e32 v4, 0xc68, v79
	ds_write2_b32 v4, v2, v3 offset1:1
	v_pk_mul_f32 v[2:3], v[36:37], v[80:81] op_sel_hi:[1,0]
	v_add_u32_e32 v4, 0x1080, v79
	ds_write2_b32 v4, v2, v3 offset1:1
	v_pk_mul_f32 v[2:3], v[38:39], v[80:81] op_sel_hi:[1,0]
	v_add_u32_e32 v4, 0x1088, v79
	ds_write2_b32 v4, v2, v3 offset1:1
	v_pk_mul_f32 v[2:3], v[32:33], v[82:83] op_sel_hi:[1,0]
	v_add_u32_e32 v4, 0x14a0, v79
	s_mul_hi_i32 s6, s11, 0x2e8ba2e9
	ds_write2_b32 v4, v2, v3 offset1:1
	v_pk_mul_f32 v[2:3], v[34:35], v[82:83] op_sel_hi:[1,0]
	v_add_u32_e32 v4, 0x14a8, v79
	s_lshr_b32 s7, s6, 31
	s_ashr_i32 s6, s6, 6
	ds_write2_b32 v4, v2, v3 offset1:1
	s_waitcnt vmcnt(7)
	v_pk_mul_f32 v[2:3], v[52:53], v[84:85] op_sel_hi:[1,0]
	v_add_u32_e32 v4, 0x18c0, v79
	s_add_i32 s11, s6, s7
	ds_write2_b32 v4, v2, v3 offset1:1
	v_pk_mul_f32 v[2:3], v[54:55], v[84:85] op_sel_hi:[1,0]
	v_add_u32_e32 v4, 0x18c8, v79
	s_lshl_b32 s6, s11, 6
	ds_write2_b32 v4, v2, v3 offset1:1
	s_waitcnt vmcnt(6)
	v_pk_mul_f32 v[2:3], v[44:45], v[86:87] op_sel_hi:[1,0]
	v_add_u32_e32 v4, 0x1ce0, v79
	ds_write2_b32 v4, v2, v3 offset1:1
	v_pk_mul_f32 v[2:3], v[46:47], v[86:87] op_sel_hi:[1,0]
	v_add_u32_e32 v4, 0x1ce8, v79
	s_ashr_i32 s7, s6, 31
	ds_write2_b32 v4, v2, v3 offset1:1
	v_lshl_add_u64 v[34:35], s[6:7], 1, v[70:71]
	s_mul_i32 s6, s11, 0xffffd400
	s_waitcnt lgkmcnt(0)
	s_add_i32 s6, s6, s8
	ds_read2_b32 v[6:7], v75 offset0:33 offset1:41
	ds_read2_b32 v[16:17], v75 offset1:8
	ds_read2_b32 v[18:19], v75 offset0:66 offset1:74
	ds_read2_b32 v[20:21], v75 offset0:99 offset1:107
	ds_read2_b32 v[22:23], v75 offset0:132 offset1:140
	ds_read2_b32 v[24:25], v75 offset0:165 offset1:173
	ds_read2_b32 v[26:27], v75 offset0:198 offset1:206
	ds_read2_b32 v[32:33], v75 offset0:231 offset1:239
	v_add_u32_e32 v38, s6, v83
	s_waitcnt lgkmcnt(6)
	v_cvt_pk_bf16_f32 v2, v16, v6
	v_add_u32_e32 v6, 0xffffea00, v38
	v_cmp_lt_i32_e32 vcc, s14, v38
	s_waitcnt lgkmcnt(4)
	v_cvt_pk_bf16_f32 v3, v18, v20
	s_waitcnt lgkmcnt(2)
	v_cvt_pk_bf16_f32 v4, v22, v24
	v_cndmask_b32_e32 v6, v38, v6, vcc
	v_lshlrev_b32_e32 v16, 1, v6
	v_and_b32_e32 v16, 0xffffff00, v16
	v_cndmask_b32_e32 v18, 0, v81, vcc
	v_and_b32_e32 v6, 0x67, v6
	v_or3_b32 v36, v6, v18, v16
	v_ashrrev_i32_e32 v37, 31, v36
	v_lshlrev_b64 v[36:37], 12, v[36:37]
	s_waitcnt lgkmcnt(0)
	v_cvt_pk_bf16_f32 v5, v26, v32
	v_lshl_add_u64 v[36:37], v[34:35], 0, v[36:37]
	v_add_u32_e32 v6, 8, v38
	global_store_dwordx4 v[36:37], v[2:5], off sc0 sc1
	v_cmp_lt_i32_e32 vcc, s14, v6
	s_waitcnt vmcnt(3)
	v_mov_b64_e32 v[52:53], v[60:61]
	v_cvt_pk_bf16_f32 v2, v17, v7
	v_add_u32_e32 v7, 0xffffea08, v38
	v_cndmask_b32_e32 v6, v6, v7, vcc
	v_lshlrev_b32_e32 v7, 1, v6
	v_and_b32_e32 v7, 0xffffff00, v7
	v_cndmask_b32_e32 v16, 0, v81, vcc
	v_and_b32_e32 v6, 0x6f, v6
	v_or3_b32 v6, v6, v16, v7
	v_ashrrev_i32_e32 v7, 31, v6
	v_lshlrev_b64 v[6:7], 12, v[6:7]
	v_cvt_pk_bf16_f32 v3, v19, v21
	v_cvt_pk_bf16_f32 v4, v23, v25
	v_cvt_pk_bf16_f32 v5, v27, v33
	v_lshl_add_u64 v[6:7], v[34:35], 0, v[6:7]
	ds_read2_b32 v[16:17], v75 offset0:16 offset1:24
	ds_read2_b32 v[18:19], v75 offset0:49 offset1:57
	ds_read2_b32 v[20:21], v75 offset0:82 offset1:90
	ds_read2_b32 v[22:23], v75 offset0:115 offset1:123
	ds_read2_b32 v[24:25], v75 offset0:148 offset1:156
	ds_read2_b32 v[26:27], v75 offset0:181 offset1:189
	ds_read2_b32 v[32:33], v75 offset0:214 offset1:222
	ds_read2_b32 v[36:37], v75 offset0:247 offset1:255
	global_store_dwordx4 v[6:7], v[2:5], off sc0 sc1
	v_add_u32_e32 v6, 16, v38
	v_add_u32_e32 v7, 0xffffea10, v38
	v_cmp_lt_i32_e32 vcc, s14, v6
	s_waitcnt lgkmcnt(6)
	v_cvt_pk_bf16_f32 v2, v16, v18
	s_waitcnt lgkmcnt(4)
	v_cvt_pk_bf16_f32 v3, v20, v22
	v_cndmask_b32_e32 v6, v6, v7, vcc
	v_lshlrev_b32_e32 v7, 1, v6
	v_and_b32_e32 v7, 0xffffff00, v7
	v_cndmask_b32_e32 v16, 0, v81, vcc
	v_and_b32_e32 v6, 0x77, v6
	v_or3_b32 v6, v6, v16, v7
	v_ashrrev_i32_e32 v7, 31, v6
	v_lshlrev_b64 v[6:7], 12, v[6:7]
	s_waitcnt lgkmcnt(2)
	v_cvt_pk_bf16_f32 v4, v24, v26
	s_waitcnt lgkmcnt(0)
	v_cvt_pk_bf16_f32 v5, v32, v36
	v_lshl_add_u64 v[6:7], v[34:35], 0, v[6:7]
	global_store_dwordx4 v[6:7], v[2:5], off sc0 sc1
	s_waitcnt vmcnt(4)
	v_mov_b64_e32 v[44:45], v[64:65]
	v_add_u32_e32 v83, s9, v83
	v_add_u32_e32 v2, 24, v38
	v_add_u32_e32 v3, 0xffffea18, v38
	v_cmp_lt_i32_e32 vcc, s14, v2
	v_cvt_pk_bf16_f32 v5, v33, v37
	v_mov_b64_e32 v[36:37], v[48:49]
	v_cndmask_b32_e32 v2, v2, v3, vcc
	v_lshlrev_b32_e32 v3, 1, v2
	v_and_b32_e32 v3, 0xffffff00, v3
	v_cndmask_b32_e32 v4, 0, v81, vcc
	v_and_b32_e32 v2, 0x7f, v2
	v_or3_b32 v6, v2, v4, v3
	v_ashrrev_i32_e32 v7, 31, v6
	v_lshlrev_b64 v[6:7], 12, v[6:7]
	v_cvt_pk_bf16_f32 v2, v17, v19
	v_cvt_pk_bf16_f32 v3, v21, v23
	v_cvt_pk_bf16_f32 v4, v25, v27
	v_lshl_add_u64 v[6:7], v[34:35], 0, v[6:7]
	global_store_dwordx4 v[6:7], v[2:5], off
	s_waitcnt lgkmcnt(0)
	v_mov_b64_e32 v[18:19], v[14:15]
	v_mov_b64_e32 v[24:25], v[28:29]
	v_mov_b64_e32 v[4:5], v[8:9]
	v_mov_b64_e32 v[20:21], v[40:41]
	v_mov_b64_e32 v[32:33], v[56:57]
	s_add_i32 s15, s15, s9
	v_add_u32_e32 v73, s9, v73
	s_andn2_b64 vcc, exec, s[0:1]
	s_mov_b32 s11, s16
	v_mov_b64_e32 v[16:17], v[12:13]
	v_mov_b64_e32 v[6:7], v[10:11]
	v_mov_b64_e32 v[26:27], v[30:31]
	v_mov_b64_e32 v[22:23], v[42:43]
	v_mov_b64_e32 v[38:39], v[50:51]
	v_mov_b64_e32 v[34:35], v[58:59]
	v_mov_b64_e32 v[54:55], v[62:63]
	v_mov_b64_e32 v[46:47], v[66:67]
	v_mov_b32_e32 v72, v85
	v_mov_b32_e32 v74, v87
	v_mov_b32_e32 v76, v89
	v_mov_b32_e32 v78, v94
	v_mov_b32_e32 v80, v95
	v_mov_b32_e32 v82, v96
	v_mov_b32_e32 v84, v97
	s_waitcnt vmcnt(4)
	v_mov_b32_e32 v86, v1
	s_cbranch_vccz .LBB0_755

; #define LAS __attribute__((address_space(3)))
; __device__ __forceinline__ unsigned cvtpk(float lo, float hi) { f32x2 v = {lo, hi}; bf16x2_t b = __builtin_convertvector(v, bf16x2_t); return __builtin_bit_cast(unsigned, b); }
; __device__ __forceinline__ void witem_store(const WItem& w, int K, bf16_t* WT, int kvperm, LAS float* scr, int item, int nblk, int lane) {
;     ...
;     for (int i = 0; i < 8; ++i) { LAS float* d = scr + (8 * i + rr) * 33 + col; const float g = w.g[i]; d[0] = w.v[i].x * g; d[1] = w.v[i].y * g; d[2] = w.v[i].z * g; d[3] = w.v[i].w * g; }
;     asm volatile("s_waitcnt lgkmcnt(0)" ::: "memory");
;     const int c = lane & 7;
; #pragma unroll
;     for (int j = 0; j < 4; ++j) { const int n = (lane >> 3) + 8 * j; const LAS float* s = scr + (8 * c) * 33 + n;
;         u32x4 o; o.x = cvtpk(s[0 * 33], s[1 * 33]); o.y = cvtpk(s[2 * 33], s[3 * 33]); o.z = cvtpk(s[4 * 33], s[5 * 33]); o.w = cvtpk(s[6 * 33], s[7 * 33]);
;         int nr = n0 + n; if (kvperm == 1) { const int hh = nr >> 8, ww = nr & 255; nr = (ww < 128) ? hh * 128 + ww : 2048 + hh * 128 + (ww - 128); }
;         else if (kvperm == 2) { const int isv = nr >= 5632, f = isv ? nr - 5632 : nr; nr = (f >> 7) * 256 + isv * 128 + (f & 127); }
;         *(u32x4*)(WT + (size_t)nr * K + k0 + 8 * c) = o; }
;     ...
;     while (it < i1) {
;         cur = nxt;
;         const int nit = it + NGW;
;         if (nit < i1) witem_load(nxt, W, N, gk, nit, nblk, lane);
;         witem_store(cur, K, WT, kvperm, scr, it, nblk, lane);
;         it = nit;
;     }
.LBB0_1205:
	v_pk_mul_f32 v[2:3], v[12:13], v[72:73] op_sel_hi:[1,0]
	ds_write2_b32 v79, v2, v3 offset1:1
	v_pk_mul_f32 v[2:3], v[14:15], v[72:73] op_sel_hi:[1,0]
	ds_write2_b32 v79, v2, v3 offset0:2 offset1:3
	v_pk_mul_f32 v[2:3], v[4:5], v[74:75] op_sel_hi:[1,0]
	v_add_u32_e32 v4, 0x420, v79
	ds_write2_b32 v4, v2, v3 offset1:1
	v_pk_mul_f32 v[2:3], v[6:7], v[74:75] op_sel_hi:[1,0]
	v_add_u32_e32 v4, 0x428, v79
	ds_write2_b32 v4, v2, v3 offset1:1
	v_pk_mul_f32 v[2:3], v[24:25], v[76:77] op_sel_hi:[1,0]
	v_add_u32_e32 v4, 0x840, v79
	ds_write2_b32 v4, v2, v3 offset1:1
	v_pk_mul_f32 v[2:3], v[26:27], v[76:77] op_sel_hi:[1,0]
	v_add_u32_e32 v4, 0x848, v79
	ds_write2_b32 v4, v2, v3 offset1:1
	v_pk_mul_f32 v[2:3], v[20:21], v[78:79] op_sel_hi:[1,0]
	v_add_u32_e32 v4, 0xc60, v79
	ds_write2_b32 v4, v2, v3 offset1:1
	v_pk_mul_f32 v[2:3], v[22:23], v[78:79] op_sel_hi:[1,0]
	v_add_u32_e32 v4, 0xc68, v79
	ds_write2_b32 v4, v2, v3 offset1:1
	v_pk_mul_f32 v[2:3], v[36:37], v[80:81] op_sel_hi:[1,0]
	v_add_u32_e32 v4, 0x1080, v79
	ds_write2_b32 v4, v2, v3 offset1:1
	v_pk_mul_f32 v[2:3], v[38:39], v[80:81] op_sel_hi:[1,0]
	v_add_u32_e32 v4, 0x1088, v79
	ds_write2_b32 v4, v2, v3 offset1:1
	v_pk_mul_f32 v[2:3], v[28:29], v[82:83] op_sel_hi:[1,0]
	v_add_u32_e32 v4, 0x14a0, v79
	ds_write2_b32 v4, v2, v3 offset1:1
	v_pk_mul_f32 v[2:3], v[30:31], v[82:83] op_sel_hi:[1,0]
	v_add_u32_e32 v4, 0x14a8, v79
	ds_write2_b32 v4, v2, v3 offset1:1
	s_waitcnt vmcnt(7)
	v_pk_mul_f32 v[2:3], v[48:49], v[84:85] op_sel_hi:[1,0]
	v_add_u32_e32 v4, 0x18c0, v79
	s_mul_hi_i32 s6, s6, 0x2e8ba2e9
	ds_write2_b32 v4, v2, v3 offset1:1
	v_pk_mul_f32 v[2:3], v[50:51], v[84:85] op_sel_hi:[1,0]
	v_add_u32_e32 v4, 0x18c8, v79
	s_lshr_b32 s10, s6, 31
	s_ashr_i32 s6, s6, 6
	ds_write2_b32 v4, v2, v3 offset1:1
	s_waitcnt vmcnt(6)
	v_pk_mul_f32 v[2:3], v[44:45], v[86:87] op_sel_hi:[1,0]
	v_add_u32_e32 v4, 0x1ce0, v79
	s_add_i32 s6, s6, s10
	ds_write2_b32 v4, v2, v3 offset1:1
	v_pk_mul_f32 v[2:3], v[46:47], v[86:87] op_sel_hi:[1,0]
	v_add_u32_e32 v4, 0x1ce8, v79
	s_lshl_b32 s10, s6, 6
	ds_write2_b32 v4, v2, v3 offset1:1
	s_mulk_i32 s6, 0xd400
	s_waitcnt lgkmcnt(0)
	s_add_i32 s6, s6, s7
	ds_read2_b32 v[6:7], v77 offset0:33 offset1:41
	ds_read2_b32 v[12:13], v77 offset1:8
	ds_read2_b32 v[14:15], v77 offset0:66 offset1:74
	ds_read2_b32 v[20:21], v77 offset0:99 offset1:107
	ds_read2_b32 v[22:23], v77 offset0:132 offset1:140
	ds_read2_b32 v[24:25], v77 offset0:165 offset1:173
	ds_read2_b32 v[26:27], v77 offset0:198 offset1:206
	ds_read2_b32 v[28:29], v77 offset0:231 offset1:239
	v_add_u32_e32 v38, s6, v83
	s_waitcnt lgkmcnt(6)
	v_cvt_pk_bf16_f32 v2, v12, v6
	v_add_u32_e32 v6, 0xffffea00, v38
	v_cmp_lt_i32_e32 vcc, s16, v38
	s_waitcnt lgkmcnt(4)
	v_cvt_pk_bf16_f32 v3, v14, v20
	s_ashr_i32 s11, s10, 31
	v_cndmask_b32_e32 v6, v38, v6, vcc
	v_lshlrev_b32_e32 v12, 1, v6
	v_and_b32_e32 v12, 0xffffff00, v12
	v_cndmask_b32_e32 v14, 0, v81, vcc
	v_and_b32_e32 v6, 0x67, v6
	v_or3_b32 v36, v6, v14, v12
	v_ashrrev_i32_e32 v37, 31, v36
	v_lshl_add_u64 v[30:31], s[10:11], 1, v[70:71]
	v_lshlrev_b64 v[36:37], 12, v[36:37]
	s_waitcnt lgkmcnt(2)
	v_cvt_pk_bf16_f32 v4, v22, v24
	s_waitcnt lgkmcnt(0)
	v_cvt_pk_bf16_f32 v5, v26, v28
	v_lshl_add_u64 v[36:37], v[30:31], 0, v[36:37]
	v_add_u32_e32 v6, 8, v38
	global_store_dwordx4 v[36:37], v[2:5], off sc0 sc1
	v_cmp_lt_i32_e32 vcc, s16, v6
	s_waitcnt vmcnt(3)
	v_mov_b64_e32 v[48:49], v[60:61]
	v_cvt_pk_bf16_f32 v2, v13, v7
	v_add_u32_e32 v7, 0xffffea08, v38
	v_cndmask_b32_e32 v6, v6, v7, vcc
	v_lshlrev_b32_e32 v7, 1, v6
	v_and_b32_e32 v7, 0xffffff00, v7
	v_cndmask_b32_e32 v12, 0, v81, vcc
	v_and_b32_e32 v6, 0x6f, v6
	v_or3_b32 v6, v6, v12, v7
	v_ashrrev_i32_e32 v7, 31, v6
	v_lshlrev_b64 v[6:7], 12, v[6:7]
	v_cvt_pk_bf16_f32 v3, v15, v21
	v_cvt_pk_bf16_f32 v4, v23, v25
	v_cvt_pk_bf16_f32 v5, v27, v29
	v_lshl_add_u64 v[6:7], v[30:31], 0, v[6:7]
	ds_read2_b32 v[12:13], v77 offset0:16 offset1:24
	ds_read2_b32 v[14:15], v77 offset0:49 offset1:57
	ds_read2_b32 v[20:21], v77 offset0:82 offset1:90
	ds_read2_b32 v[22:23], v77 offset0:115 offset1:123
	ds_read2_b32 v[24:25], v77 offset0:148 offset1:156
	ds_read2_b32 v[26:27], v77 offset0:181 offset1:189
	ds_read2_b32 v[28:29], v77 offset0:214 offset1:222
	ds_read2_b32 v[36:37], v77 offset0:247 offset1:255
	global_store_dwordx4 v[6:7], v[2:5], off sc0 sc1
	v_add_u32_e32 v6, 16, v38
	v_add_u32_e32 v7, 0xffffea10, v38
	v_cmp_lt_i32_e32 vcc, s16, v6
	s_waitcnt lgkmcnt(6)
	v_cvt_pk_bf16_f32 v2, v12, v14
	s_waitcnt lgkmcnt(4)
	v_cvt_pk_bf16_f32 v3, v20, v22
	v_cndmask_b32_e32 v6, v6, v7, vcc
	v_lshlrev_b32_e32 v7, 1, v6
	v_and_b32_e32 v7, 0xffffff00, v7
	v_cndmask_b32_e32 v12, 0, v81, vcc
	v_and_b32_e32 v6, 0x77, v6
	v_or3_b32 v6, v6, v12, v7
	v_ashrrev_i32_e32 v7, 31, v6
	v_lshlrev_b64 v[6:7], 12, v[6:7]
	s_waitcnt lgkmcnt(2)
	v_cvt_pk_bf16_f32 v4, v24, v26
	s_waitcnt lgkmcnt(0)
	v_cvt_pk_bf16_f32 v5, v28, v36
	v_lshl_add_u64 v[6:7], v[30:31], 0, v[6:7]
	global_store_dwordx4 v[6:7], v[2:5], off sc0 sc1
	s_waitcnt vmcnt(4)
	v_mov_b64_e32 v[44:45], v[64:65]
	v_add_u32_e32 v83, s12, v83
	v_add_u32_e32 v2, 24, v38
	v_add_u32_e32 v3, 0xffffea18, v38
	v_cmp_lt_i32_e32 vcc, s16, v2
	v_cvt_pk_bf16_f32 v5, v29, v37
	v_mov_b64_e32 v[36:37], v[52:53]
	v_cndmask_b32_e32 v2, v2, v3, vcc
	v_lshlrev_b32_e32 v3, 1, v2
	v_and_b32_e32 v3, 0xffffff00, v3
	v_cndmask_b32_e32 v4, 0, v81, vcc
	v_and_b32_e32 v2, 0x7f, v2
	v_or3_b32 v6, v2, v4, v3
	v_ashrrev_i32_e32 v7, 31, v6
	v_lshlrev_b64 v[6:7], 12, v[6:7]
	v_cvt_pk_bf16_f32 v2, v13, v15
	v_cvt_pk_bf16_f32 v3, v21, v23
	v_cvt_pk_bf16_f32 v4, v25, v27
	v_lshl_add_u64 v[6:7], v[30:31], 0, v[6:7]
	global_store_dwordx4 v[6:7], v[2:5], off
	s_waitcnt lgkmcnt(0)
	v_mov_b64_e32 v[12:13], v[16:17]
	v_mov_b64_e32 v[24:25], v[32:33]
	v_mov_b64_e32 v[4:5], v[8:9]
	v_mov_b64_e32 v[20:21], v[40:41]
	v_mov_b64_e32 v[28:29], v[56:57]
	s_add_i32 s17, s17, s12
	v_add_u32_e32 v73, s12, v73
	s_andn2_b64 vcc, exec, s[8:9]
	s_mov_b32 s6, s18
	v_mov_b64_e32 v[14:15], v[18:19]
	v_mov_b64_e32 v[6:7], v[10:11]
	v_mov_b64_e32 v[26:27], v[34:35]
	v_mov_b64_e32 v[22:23], v[42:43]
	v_mov_b64_e32 v[38:39], v[54:55]
	v_mov_b64_e32 v[30:31], v[58:59]
	v_mov_b64_e32 v[50:51], v[62:63]
	v_mov_b64_e32 v[46:47], v[66:67]
	v_mov_b32_e32 v72, v85
	v_mov_b32_e32 v74, v87
	v_mov_b32_e32 v76, v89
	v_mov_b32_e32 v78, v94
	v_mov_b32_e32 v80, v95
	v_mov_b32_e32 v82, v96
	v_mov_b32_e32 v84, v97
	s_waitcnt vmcnt(4)
	v_mov_b32_e32 v86, v1
	s_cbranch_vccz .LBB0_1223

; #define LAS __attribute__((address_space(3)))
; __device__ __forceinline__ unsigned cvtpk(float lo, float hi) { f32x2 v = {lo, hi}; bf16x2_t b = __builtin_convertvector(v, bf16x2_t); return __builtin_bit_cast(unsigned, b); }
; __device__ __forceinline__ void witem_store(const WItem& w, int K, bf16_t* WT, int kvperm, LAS float* scr, int item, int nblk, int lane) {
;     ...
;     for (int i = 0; i < 8; ++i) { LAS float* d = scr + (8 * i + rr) * 33 + col; const float g = w.g[i]; d[0] = w.v[i].x * g; d[1] = w.v[i].y * g; d[2] = w.v[i].z * g; d[3] = w.v[i].w * g; }
;     asm volatile("s_waitcnt lgkmcnt(0)" ::: "memory");
;     const int c = lane & 7;
; #pragma unroll
;     for (int j = 0; j < 4; ++j) { const int n = (lane >> 3) + 8 * j; const LAS float* s = scr + (8 * c) * 33 + n;
;         u32x4 o; o.x = cvtpk(s[0 * 33], s[1 * 33]); o.y = cvtpk(s[2 * 33], s[3 * 33]); o.z = cvtpk(s[4 * 33], s[5 * 33]); o.w = cvtpk(s[6 * 33], s[7 * 33]);
;         int nr = n0 + n; if (kvperm == 1) { const int hh = nr >> 8, ww = nr & 255; nr = (ww < 128) ? hh * 128 + ww : 2048 + hh * 128 + (ww - 128); }
;         else if (kvperm == 2) { const int isv = nr >= 5632, f = isv ? nr - 5632 : nr; nr = (f >> 7) * 256 + isv * 128 + (f & 127); }
;         *(u32x4*)(WT + (size_t)nr * K + k0 + 8 * c) = o; }
;     ...
;     while (it < i1) {
;         cur = nxt;
;         const int nit = it + NGW;
;         if (nit < i1) witem_load(nxt, W, N, gk, nit, nblk, lane);
;         witem_store(cur, K, WT, kvperm, scr, it, nblk, lane);
;         it = nit;
;     }
.LBB0_1491:
	v_pk_mul_f32 v[2:3], v[16:17], v[72:73] op_sel_hi:[1,0]
	ds_write2_b32 v85, v2, v3 offset1:1
	v_pk_mul_f32 v[2:3], v[18:19], v[72:73] op_sel_hi:[1,0]
	ds_write2_b32 v85, v2, v3 offset0:2 offset1:3
	v_pk_mul_f32 v[2:3], v[4:5], v[74:75] op_sel_hi:[1,0]
	v_add_u32_e32 v4, 0x420, v85
	ds_write2_b32 v4, v2, v3 offset1:1
	v_pk_mul_f32 v[2:3], v[6:7], v[74:75] op_sel_hi:[1,0]
	v_add_u32_e32 v4, 0x428, v85
	ds_write2_b32 v4, v2, v3 offset1:1
	v_pk_mul_f32 v[2:3], v[24:25], v[76:77] op_sel_hi:[1,0]
	v_add_u32_e32 v4, 0x840, v85
	ds_write2_b32 v4, v2, v3 offset1:1
	v_pk_mul_f32 v[2:3], v[26:27], v[76:77] op_sel_hi:[1,0]
	v_add_u32_e32 v4, 0x848, v85
	ds_write2_b32 v4, v2, v3 offset1:1
	v_pk_mul_f32 v[2:3], v[20:21], v[78:79] op_sel_hi:[1,0]
	v_add_u32_e32 v4, 0xc60, v85
	ds_write2_b32 v4, v2, v3 offset1:1
	v_pk_mul_f32 v[2:3], v[22:23], v[78:79] op_sel_hi:[1,0]
	v_add_u32_e32 v4, 0xc68, v85
	ds_write2_b32 v4, v2, v3 offset1:1
	v_pk_mul_f32 v[2:3], v[36:37], v[80:81] op_sel_hi:[1,0]
	v_add_u32_e32 v4, 0x1080, v85
	ds_write2_b32 v4, v2, v3 offset1:1
	v_pk_mul_f32 v[2:3], v[38:39], v[80:81] op_sel_hi:[1,0]
	v_add_u32_e32 v4, 0x1088, v85
	ds_write2_b32 v4, v2, v3 offset1:1
	v_pk_mul_f32 v[2:3], v[32:33], v[82:83] op_sel_hi:[1,0]
	v_add_u32_e32 v4, 0x14a0, v85
	s_mul_hi_i32 s16, s27, 0x2e8ba2e9
	ds_write2_b32 v4, v2, v3 offset1:1
	v_pk_mul_f32 v[2:3], v[34:35], v[82:83] op_sel_hi:[1,0]
	v_add_u32_e32 v4, 0x14a8, v85
	s_lshr_b32 s17, s16, 31
	s_ashr_i32 s16, s16, 6
	ds_write2_b32 v4, v2, v3 offset1:1
	v_pk_mul_f32 v[2:3], v[52:53], v[84:85] op_sel_hi:[1,0]
	v_add_u32_e32 v4, 0x18c0, v85
	s_add_i32 s27, s16, s17
	ds_write2_b32 v4, v2, v3 offset1:1
	v_pk_mul_f32 v[2:3], v[54:55], v[84:85] op_sel_hi:[1,0]
	v_add_u32_e32 v4, 0x18c8, v85
	s_lshl_b32 s16, s27, 6
	ds_write2_b32 v4, v2, v3 offset1:1
	v_pk_mul_f32 v[2:3], v[44:45], v[86:87] op_sel_hi:[1,0]
	v_add_u32_e32 v4, 0x1ce0, v85
	ds_write2_b32 v4, v2, v3 offset1:1
	v_pk_mul_f32 v[2:3], v[46:47], v[86:87] op_sel_hi:[1,0]
	v_add_u32_e32 v4, 0x1ce8, v85
	s_ashr_i32 s17, s16, 31
	ds_write2_b32 v4, v2, v3 offset1:1
	v_lshl_add_u64 v[34:35], s[16:17], 1, v[70:71]
	s_mul_i32 s16, s27, 0xffffd400
	s_waitcnt lgkmcnt(0)
	s_add_i32 s16, s16, s22
	ds_read2_b32 v[6:7], v83 offset0:33 offset1:41
	ds_read2_b32 v[16:17], v83 offset1:8
	ds_read2_b32 v[18:19], v83 offset0:66 offset1:74
	ds_read2_b32 v[20:21], v83 offset0:99 offset1:107
	ds_read2_b32 v[22:23], v83 offset0:132 offset1:140
	ds_read2_b32 v[24:25], v83 offset0:165 offset1:173
	ds_read2_b32 v[26:27], v83 offset0:198 offset1:206
	ds_read2_b32 v[32:33], v83 offset0:231 offset1:239
	v_add_u32_e32 v38, s16, v94
	s_waitcnt lgkmcnt(6)
	v_cvt_pk_bf16_f32 v2, v16, v6
	v_add_u32_e32 v6, 0xffffea00, v38
	v_cmp_lt_i32_e32 vcc, s28, v38
	s_waitcnt lgkmcnt(4)
	v_cvt_pk_bf16_f32 v3, v18, v20
	s_waitcnt lgkmcnt(2)
	v_cvt_pk_bf16_f32 v4, v22, v24
	v_cndmask_b32_e32 v6, v38, v6, vcc
	v_lshlrev_b32_e32 v16, 1, v6
	v_and_b32_e32 v16, 0xffffff00, v16
	v_cndmask_b32_e32 v18, 0, v87, vcc
	v_and_b32_e32 v6, 0x67, v6
	v_or3_b32 v36, v6, v18, v16
	v_ashrrev_i32_e32 v37, 31, v36
	v_lshlrev_b64 v[36:37], 12, v[36:37]
	s_waitcnt lgkmcnt(0)
	v_cvt_pk_bf16_f32 v5, v26, v32
	v_lshl_add_u64 v[36:37], v[34:35], 0, v[36:37]
	v_add_u32_e32 v6, 8, v38
	global_store_dwordx4 v[36:37], v[2:5], off sc0 sc1
	v_cmp_lt_i32_e32 vcc, s28, v6
	s_waitcnt vmcnt(3)
	v_mov_b64_e32 v[52:53], v[60:61]
	v_cvt_pk_bf16_f32 v2, v17, v7
	v_add_u32_e32 v7, 0xffffea08, v38
	v_cndmask_b32_e32 v6, v6, v7, vcc
	v_lshlrev_b32_e32 v7, 1, v6
	v_and_b32_e32 v7, 0xffffff00, v7
	v_cndmask_b32_e32 v16, 0, v87, vcc
	v_and_b32_e32 v6, 0x6f, v6
	v_or3_b32 v6, v6, v16, v7
	v_ashrrev_i32_e32 v7, 31, v6
	v_lshlrev_b64 v[6:7], 12, v[6:7]
	v_cvt_pk_bf16_f32 v3, v19, v21
	v_cvt_pk_bf16_f32 v4, v23, v25
	v_cvt_pk_bf16_f32 v5, v27, v33
	v_lshl_add_u64 v[6:7], v[34:35], 0, v[6:7]
	ds_read2_b32 v[16:17], v83 offset0:16 offset1:24
	ds_read2_b32 v[18:19], v83 offset0:49 offset1:57
	ds_read2_b32 v[20:21], v83 offset0:82 offset1:90
	ds_read2_b32 v[22:23], v83 offset0:115 offset1:123
	ds_read2_b32 v[24:25], v83 offset0:148 offset1:156
	ds_read2_b32 v[26:27], v83 offset0:181 offset1:189
	ds_read2_b32 v[32:33], v83 offset0:214 offset1:222
	ds_read2_b32 v[36:37], v83 offset0:247 offset1:255
	global_store_dwordx4 v[6:7], v[2:5], off sc0 sc1
	v_add_u32_e32 v6, 16, v38
	v_add_u32_e32 v7, 0xffffea10, v38
	v_cmp_lt_i32_e32 vcc, s28, v6
	s_waitcnt lgkmcnt(6)
	v_cvt_pk_bf16_f32 v2, v16, v18
	s_waitcnt lgkmcnt(4)
	v_cvt_pk_bf16_f32 v3, v20, v22
	v_cndmask_b32_e32 v6, v6, v7, vcc
	v_lshlrev_b32_e32 v7, 1, v6
	v_and_b32_e32 v7, 0xffffff00, v7
	v_cndmask_b32_e32 v16, 0, v87, vcc
	v_and_b32_e32 v6, 0x77, v6
	v_or3_b32 v6, v6, v16, v7
	v_ashrrev_i32_e32 v7, 31, v6
	v_lshlrev_b64 v[6:7], 12, v[6:7]
	s_waitcnt lgkmcnt(2)
	v_cvt_pk_bf16_f32 v4, v24, v26
	s_waitcnt lgkmcnt(0)
	v_cvt_pk_bf16_f32 v5, v32, v36
	v_lshl_add_u64 v[6:7], v[34:35], 0, v[6:7]
	global_store_dwordx4 v[6:7], v[2:5], off sc0 sc1
	s_waitcnt vmcnt(4)
	v_mov_b64_e32 v[44:45], v[64:65]
	v_add_u32_e32 v94, s23, v94
	v_add_u32_e32 v2, 24, v38
	v_add_u32_e32 v3, 0xffffea18, v38
	v_cmp_lt_i32_e32 vcc, s28, v2
	v_cvt_pk_bf16_f32 v5, v33, v37
	v_mov_b64_e32 v[36:37], v[48:49]
	v_cndmask_b32_e32 v2, v2, v3, vcc
	v_lshlrev_b32_e32 v3, 1, v2
	v_and_b32_e32 v3, 0xffffff00, v3
	v_cndmask_b32_e32 v4, 0, v87, vcc
	v_and_b32_e32 v2, 0x7f, v2
	v_or3_b32 v6, v2, v4, v3
	v_ashrrev_i32_e32 v7, 31, v6
	v_lshlrev_b64 v[6:7], 12, v[6:7]
	v_cvt_pk_bf16_f32 v2, v17, v19
	v_cvt_pk_bf16_f32 v3, v21, v23
	v_cvt_pk_bf16_f32 v4, v25, v27
	v_lshl_add_u64 v[6:7], v[34:35], 0, v[6:7]
	global_store_dwordx4 v[6:7], v[2:5], off
	s_waitcnt lgkmcnt(0)
	v_mov_b64_e32 v[18:19], v[14:15]
	v_mov_b64_e32 v[24:25], v[28:29]
	v_mov_b64_e32 v[4:5], v[8:9]
	v_mov_b64_e32 v[20:21], v[40:41]
	v_mov_b64_e32 v[32:33], v[56:57]
	s_add_i32 s29, s29, s23
	v_add_u32_e32 v73, s23, v73
	s_andn2_b64 vcc, exec, s[14:15]
	s_mov_b32 s27, s30
	v_mov_b64_e32 v[16:17], v[12:13]
	v_mov_b64_e32 v[6:7], v[10:11]
	v_mov_b64_e32 v[26:27], v[30:31]
	v_mov_b64_e32 v[22:23], v[42:43]
	v_mov_b64_e32 v[38:39], v[50:51]
	v_mov_b64_e32 v[34:35], v[58:59]
	v_mov_b64_e32 v[54:55], v[62:63]
	v_mov_b64_e32 v[46:47], v[66:67]
	v_mov_b32_e32 v72, v89
	v_mov_b32_e32 v74, v95
	v_mov_b32_e32 v76, v96
	v_mov_b32_e32 v78, v97
	v_mov_b32_e32 v80, v98
	v_mov_b32_e32 v82, v99
	v_mov_b32_e32 v84, v100
	s_waitcnt vmcnt(4)
	v_mov_b32_e32 v86, v1
	s_cbranch_vccz .LBB0_1509

; #define LAS __attribute__((address_space(3)))
; __device__ __forceinline__ unsigned cvtpk(float lo, float hi) { f32x2 v = {lo, hi}; bf16x2_t b = __builtin_convertvector(v, bf16x2_t); return __builtin_bit_cast(unsigned, b); }
; __device__ __forceinline__ void witem_store(const WItem& w, int K, bf16_t* WT, int kvperm, LAS float* scr, int item, int nblk, int lane) {
;     ...
;     for (int i = 0; i < 8; ++i) { LAS float* d = scr + (8 * i + rr) * 33 + col; const float g = w.g[i]; d[0] = w.v[i].x * g; d[1] = w.v[i].y * g; d[2] = w.v[i].z * g; d[3] = w.v[i].w * g; }
;     asm volatile("s_waitcnt lgkmcnt(0)" ::: "memory");
;     const int c = lane & 7;
; #pragma unroll
;     for (int j = 0; j < 4; ++j) { const int n = (lane >> 3) + 8 * j; const LAS float* s = scr + (8 * c) * 33 + n;
;         u32x4 o; o.x = cvtpk(s[0 * 33], s[1 * 33]); o.y = cvtpk(s[2 * 33], s[3 * 33]); o.z = cvtpk(s[4 * 33], s[5 * 33]); o.w = cvtpk(s[6 * 33], s[7 * 33]);
;         int nr = n0 + n; if (kvperm == 1) { const int hh = nr >> 8, ww = nr & 255; nr = (ww < 128) ? hh * 128 + ww : 2048 + hh * 128 + (ww - 128); }
;         else if (kvperm == 2) { const int isv = nr >= 5632, f = isv ? nr - 5632 : nr; nr = (f >> 7) * 256 + isv * 128 + (f & 127); }
;         *(u32x4*)(WT + (size_t)nr * K + k0 + 8 * c) = o; }
;     ...
;     while (it < i1) {
;         cur = nxt;
;         const int nit = it + NGW;
;         if (nit < i1) witem_load(nxt, W, N, gk, nit, nblk, lane);
;         witem_store(cur, K, WT, kvperm, scr, it, nblk, lane);
;         it = nit;
;     }
.LBB0_1528:
	v_pk_mul_f32 v[2:3], v[16:17], v[72:73] op_sel_hi:[1,0]
	ds_write2_b32 v79, v2, v3 offset1:1
	v_pk_mul_f32 v[2:3], v[18:19], v[72:73] op_sel_hi:[1,0]
	ds_write2_b32 v79, v2, v3 offset0:2 offset1:3
	v_pk_mul_f32 v[2:3], v[4:5], v[74:75] op_sel_hi:[1,0]
	v_add_u32_e32 v4, 0x420, v79
	ds_write2_b32 v4, v2, v3 offset1:1
	v_pk_mul_f32 v[2:3], v[6:7], v[74:75] op_sel_hi:[1,0]
	v_add_u32_e32 v4, 0x428, v79
	ds_write2_b32 v4, v2, v3 offset1:1
	v_pk_mul_f32 v[2:3], v[24:25], v[76:77] op_sel_hi:[1,0]
	v_add_u32_e32 v4, 0x840, v79
	ds_write2_b32 v4, v2, v3 offset1:1
	v_pk_mul_f32 v[2:3], v[26:27], v[76:77] op_sel_hi:[1,0]
	v_add_u32_e32 v4, 0x848, v79
	ds_write2_b32 v4, v2, v3 offset1:1
	v_pk_mul_f32 v[2:3], v[20:21], v[78:79] op_sel_hi:[1,0]
	v_add_u32_e32 v4, 0xc60, v79
	ds_write2_b32 v4, v2, v3 offset1:1
	v_pk_mul_f32 v[2:3], v[22:23], v[78:79] op_sel_hi:[1,0]
	v_add_u32_e32 v4, 0xc68, v79
	ds_write2_b32 v4, v2, v3 offset1:1
	v_pk_mul_f32 v[2:3], v[36:37], v[80:81] op_sel_hi:[1,0]
	v_add_u32_e32 v4, 0x1080, v79
	ds_write2_b32 v4, v2, v3 offset1:1
	v_pk_mul_f32 v[2:3], v[38:39], v[80:81] op_sel_hi:[1,0]
	v_add_u32_e32 v4, 0x1088, v79
	ds_write2_b32 v4, v2, v3 offset1:1
	v_pk_mul_f32 v[2:3], v[32:33], v[82:83] op_sel_hi:[1,0]
	v_add_u32_e32 v4, 0x14a0, v79
	s_mul_hi_i32 s10, s15, 0x2e8ba2e9
	ds_write2_b32 v4, v2, v3 offset1:1
	v_pk_mul_f32 v[2:3], v[34:35], v[82:83] op_sel_hi:[1,0]
	v_add_u32_e32 v4, 0x14a8, v79
	s_lshr_b32 s11, s10, 31
	s_ashr_i32 s10, s10, 6
	ds_write2_b32 v4, v2, v3 offset1:1
	s_waitcnt vmcnt(7)
	v_pk_mul_f32 v[2:3], v[52:53], v[84:85] op_sel_hi:[1,0]
	v_add_u32_e32 v4, 0x18c0, v79
	s_add_i32 s15, s10, s11
	ds_write2_b32 v4, v2, v3 offset1:1
	v_pk_mul_f32 v[2:3], v[54:55], v[84:85] op_sel_hi:[1,0]
	v_add_u32_e32 v4, 0x18c8, v79
	s_lshl_b32 s10, s15, 6
	ds_write2_b32 v4, v2, v3 offset1:1
	s_waitcnt vmcnt(6)
	v_pk_mul_f32 v[2:3], v[44:45], v[86:87] op_sel_hi:[1,0]
	v_add_u32_e32 v4, 0x1ce0, v79
	ds_write2_b32 v4, v2, v3 offset1:1
	v_pk_mul_f32 v[2:3], v[46:47], v[86:87] op_sel_hi:[1,0]
	v_add_u32_e32 v4, 0x1ce8, v79
	s_ashr_i32 s11, s10, 31
	ds_write2_b32 v4, v2, v3 offset1:1
	v_lshl_add_u64 v[34:35], s[10:11], 1, v[70:71]
	s_mul_i32 s10, s15, 0xffffd400
	s_waitcnt lgkmcnt(0)
	s_add_i32 s10, s10, s2
	ds_read2_b32 v[6:7], v75 offset0:33 offset1:41
	ds_read2_b32 v[16:17], v75 offset1:8
	ds_read2_b32 v[18:19], v75 offset0:66 offset1:74
	ds_read2_b32 v[20:21], v75 offset0:99 offset1:107
	ds_read2_b32 v[22:23], v75 offset0:132 offset1:140
	ds_read2_b32 v[24:25], v75 offset0:165 offset1:173
	ds_read2_b32 v[26:27], v75 offset0:198 offset1:206
	ds_read2_b32 v[32:33], v75 offset0:231 offset1:239
	v_add_u32_e32 v38, s10, v83
	s_waitcnt lgkmcnt(6)
	v_cvt_pk_bf16_f32 v2, v16, v6
	v_add_u32_e32 v6, 0xffffea00, v38
	v_cmp_lt_i32_e32 vcc, s14, v38
	s_waitcnt lgkmcnt(4)
	v_cvt_pk_bf16_f32 v3, v18, v20
	s_waitcnt lgkmcnt(2)
	v_cvt_pk_bf16_f32 v4, v22, v24
	v_cndmask_b32_e32 v6, v38, v6, vcc
	v_lshlrev_b32_e32 v16, 1, v6
	v_and_b32_e32 v16, 0xffffff00, v16
	v_cndmask_b32_e32 v18, 0, v81, vcc
	v_and_b32_e32 v6, 0x67, v6
	v_or3_b32 v36, v6, v18, v16
	v_ashrrev_i32_e32 v37, 31, v36
	v_lshlrev_b64 v[36:37], 12, v[36:37]
	s_waitcnt lgkmcnt(0)
	v_cvt_pk_bf16_f32 v5, v26, v32
	v_lshl_add_u64 v[36:37], v[34:35], 0, v[36:37]
	v_add_u32_e32 v6, 8, v38
	global_store_dwordx4 v[36:37], v[2:5], off sc0 sc1
	v_cmp_lt_i32_e32 vcc, s14, v6
	s_waitcnt vmcnt(3)
	v_mov_b64_e32 v[52:53], v[60:61]
	v_cvt_pk_bf16_f32 v2, v17, v7
	v_add_u32_e32 v7, 0xffffea08, v38
	v_cndmask_b32_e32 v6, v6, v7, vcc
	v_lshlrev_b32_e32 v7, 1, v6
	v_and_b32_e32 v7, 0xffffff00, v7
	v_cndmask_b32_e32 v16, 0, v81, vcc
	v_and_b32_e32 v6, 0x6f, v6
	v_or3_b32 v6, v6, v16, v7
	v_ashrrev_i32_e32 v7, 31, v6
	v_lshlrev_b64 v[6:7], 12, v[6:7]
	v_cvt_pk_bf16_f32 v3, v19, v21
	v_cvt_pk_bf16_f32 v4, v23, v25
	v_cvt_pk_bf16_f32 v5, v27, v33
	v_lshl_add_u64 v[6:7], v[34:35], 0, v[6:7]
	ds_read2_b32 v[16:17], v75 offset0:16 offset1:24
	ds_read2_b32 v[18:19], v75 offset0:49 offset1:57
	ds_read2_b32 v[20:21], v75 offset0:82 offset1:90
	ds_read2_b32 v[22:23], v75 offset0:115 offset1:123
	ds_read2_b32 v[24:25], v75 offset0:148 offset1:156
	ds_read2_b32 v[26:27], v75 offset0:181 offset1:189
	ds_read2_b32 v[32:33], v75 offset0:214 offset1:222
	ds_read2_b32 v[36:37], v75 offset0:247 offset1:255
	global_store_dwordx4 v[6:7], v[2:5], off sc0 sc1
	v_add_u32_e32 v6, 16, v38
	v_add_u32_e32 v7, 0xffffea10, v38
	v_cmp_lt_i32_e32 vcc, s14, v6
	s_waitcnt lgkmcnt(6)
	v_cvt_pk_bf16_f32 v2, v16, v18
	s_waitcnt lgkmcnt(4)
	v_cvt_pk_bf16_f32 v3, v20, v22
	v_cndmask_b32_e32 v6, v6, v7, vcc
	v_lshlrev_b32_e32 v7, 1, v6
	v_and_b32_e32 v7, 0xffffff00, v7
	v_cndmask_b32_e32 v16, 0, v81, vcc
	v_and_b32_e32 v6, 0x77, v6
	v_or3_b32 v6, v6, v16, v7
	v_ashrrev_i32_e32 v7, 31, v6
	v_lshlrev_b64 v[6:7], 12, v[6:7]
	s_waitcnt lgkmcnt(2)
	v_cvt_pk_bf16_f32 v4, v24, v26
	s_waitcnt lgkmcnt(0)
	v_cvt_pk_bf16_f32 v5, v32, v36
	v_lshl_add_u64 v[6:7], v[34:35], 0, v[6:7]
	global_store_dwordx4 v[6:7], v[2:5], off sc0 sc1
	s_waitcnt vmcnt(4)
	v_mov_b64_e32 v[44:45], v[64:65]
	v_add_u32_e32 v83, s6, v83
	v_add_u32_e32 v2, 24, v38
	v_add_u32_e32 v3, 0xffffea18, v38
	v_cmp_lt_i32_e32 vcc, s14, v2
	v_cvt_pk_bf16_f32 v5, v33, v37
	v_mov_b64_e32 v[36:37], v[48:49]
	v_cndmask_b32_e32 v2, v2, v3, vcc
	v_lshlrev_b32_e32 v3, 1, v2
	v_and_b32_e32 v3, 0xffffff00, v3
	v_cndmask_b32_e32 v4, 0, v81, vcc
	v_and_b32_e32 v2, 0x7f, v2
	v_or3_b32 v6, v2, v4, v3
	v_ashrrev_i32_e32 v7, 31, v6
	v_lshlrev_b64 v[6:7], 12, v[6:7]
	v_cvt_pk_bf16_f32 v2, v17, v19
	v_cvt_pk_bf16_f32 v3, v21, v23
	v_cvt_pk_bf16_f32 v4, v25, v27
	v_lshl_add_u64 v[6:7], v[34:35], 0, v[6:7]
	global_store_dwordx4 v[6:7], v[2:5], off
	s_waitcnt lgkmcnt(0)
	v_mov_b64_e32 v[18:19], v[14:15]
	v_mov_b64_e32 v[24:25], v[28:29]
	v_mov_b64_e32 v[4:5], v[8:9]
	v_mov_b64_e32 v[20:21], v[40:41]
	v_mov_b64_e32 v[32:33], v[56:57]
	s_add_i32 s16, s16, s6
	v_add_u32_e32 v73, s6, v73
	s_andn2_b64 vcc, exec, s[0:1]
	s_mov_b32 s15, s17
	v_mov_b64_e32 v[16:17], v[12:13]
	v_mov_b64_e32 v[6:7], v[10:11]
	v_mov_b64_e32 v[26:27], v[30:31]
	v_mov_b64_e32 v[22:23], v[42:43]
	v_mov_b64_e32 v[38:39], v[50:51]
	v_mov_b64_e32 v[34:35], v[58:59]
	v_mov_b64_e32 v[54:55], v[62:63]
	v_mov_b64_e32 v[46:47], v[66:67]
	v_mov_b32_e32 v72, v85
	v_mov_b32_e32 v74, v87
	v_mov_b32_e32 v76, v89
	v_mov_b32_e32 v78, v94
	v_mov_b32_e32 v80, v95
	v_mov_b32_e32 v82, v96
	v_mov_b32_e32 v84, v97
	s_waitcnt vmcnt(4)
	v_mov_b32_e32 v86, v1
	s_cbranch_vccz .LBB0_1546

; #define LAS __attribute__((address_space(3)))
; __device__ __forceinline__ unsigned cvtpk(float lo, float hi) { f32x2 v = {lo, hi}; bf16x2_t b = __builtin_convertvector(v, bf16x2_t); return __builtin_bit_cast(unsigned, b); }
; __device__ __forceinline__ void witem_store(const WItem& w, int K, bf16_t* WT, int kvperm, LAS float* scr, int item, int nblk, int lane) {
;     ...
;     for (int i = 0; i < 8; ++i) { LAS float* d = scr + (8 * i + rr) * 33 + col; const float g = w.g[i]; d[0] = w.v[i].x * g; d[1] = w.v[i].y * g; d[2] = w.v[i].z * g; d[3] = w.v[i].w * g; }
;     asm volatile("s_waitcnt lgkmcnt(0)" ::: "memory");
;     const int c = lane & 7;
; #pragma unroll
;     for (int j = 0; j < 4; ++j) { const int n = (lane >> 3) + 8 * j; const LAS float* s = scr + (8 * c) * 33 + n;
;         u32x4 o; o.x = cvtpk(s[0 * 33], s[1 * 33]); o.y = cvtpk(s[2 * 33], s[3 * 33]); o.z = cvtpk(s[4 * 33], s[5 * 33]); o.w = cvtpk(s[6 * 33], s[7 * 33]);
;         int nr = n0 + n; if (kvperm == 1) { const int hh = nr >> 8, ww = nr & 255; nr = (ww < 128) ? hh * 128 + ww : 2048 + hh * 128 + (ww - 128); }
;         else if (kvperm == 2) { const int isv = nr >= 5632, f = isv ? nr - 5632 : nr; nr = (f >> 7) * 256 + isv * 128 + (f & 127); }
;         *(u32x4*)(WT + (size_t)nr * K + k0 + 8 * c) = o; }
;     ...
;     while (it < i1) {
;         cur = nxt;
;         const int nit = it + NGW;
;         if (nit < i1) witem_load(nxt, W, N, gk, nit, nblk, lane);
;         witem_store(cur, K, WT, kvperm, scr, it, nblk, lane);
;         it = nit;
;     }
.LBB0_1844:
	v_pk_mul_f32 v[2:3], v[12:13], v[72:73] op_sel_hi:[1,0]
	ds_write2_b32 v79, v2, v3 offset1:1
	v_pk_mul_f32 v[2:3], v[14:15], v[72:73] op_sel_hi:[1,0]
	ds_write2_b32 v79, v2, v3 offset0:2 offset1:3
	v_pk_mul_f32 v[2:3], v[4:5], v[74:75] op_sel_hi:[1,0]
	v_add_u32_e32 v4, 0x420, v79
	ds_write2_b32 v4, v2, v3 offset1:1
	v_pk_mul_f32 v[2:3], v[6:7], v[74:75] op_sel_hi:[1,0]
	v_add_u32_e32 v4, 0x428, v79
	ds_write2_b32 v4, v2, v3 offset1:1
	v_pk_mul_f32 v[2:3], v[24:25], v[76:77] op_sel_hi:[1,0]
	v_add_u32_e32 v4, 0x840, v79
	ds_write2_b32 v4, v2, v3 offset1:1
	v_pk_mul_f32 v[2:3], v[26:27], v[76:77] op_sel_hi:[1,0]
	v_add_u32_e32 v4, 0x848, v79
	ds_write2_b32 v4, v2, v3 offset1:1
	v_pk_mul_f32 v[2:3], v[20:21], v[78:79] op_sel_hi:[1,0]
	v_add_u32_e32 v4, 0xc60, v79
	ds_write2_b32 v4, v2, v3 offset1:1
	v_pk_mul_f32 v[2:3], v[22:23], v[78:79] op_sel_hi:[1,0]
	v_add_u32_e32 v4, 0xc68, v79
	ds_write2_b32 v4, v2, v3 offset1:1
	v_pk_mul_f32 v[2:3], v[36:37], v[80:81] op_sel_hi:[1,0]
	v_add_u32_e32 v4, 0x1080, v79
	ds_write2_b32 v4, v2, v3 offset1:1
	v_pk_mul_f32 v[2:3], v[38:39], v[80:81] op_sel_hi:[1,0]
	v_add_u32_e32 v4, 0x1088, v79
	ds_write2_b32 v4, v2, v3 offset1:1
	v_pk_mul_f32 v[2:3], v[28:29], v[82:83] op_sel_hi:[1,0]
	v_add_u32_e32 v4, 0x14a0, v79
	ds_write2_b32 v4, v2, v3 offset1:1
	v_pk_mul_f32 v[2:3], v[30:31], v[82:83] op_sel_hi:[1,0]
	v_add_u32_e32 v4, 0x14a8, v79
	ds_write2_b32 v4, v2, v3 offset1:1
	s_waitcnt vmcnt(7)
	v_pk_mul_f32 v[2:3], v[48:49], v[84:85] op_sel_hi:[1,0]
	v_add_u32_e32 v4, 0x18c0, v79
	s_mul_hi_i32 s6, s6, 0x2e8ba2e9
	ds_write2_b32 v4, v2, v3 offset1:1
	v_pk_mul_f32 v[2:3], v[50:51], v[84:85] op_sel_hi:[1,0]
	v_add_u32_e32 v4, 0x18c8, v79
	s_lshr_b32 s12, s6, 31
	s_ashr_i32 s6, s6, 6
	ds_write2_b32 v4, v2, v3 offset1:1
	s_waitcnt vmcnt(6)
	v_pk_mul_f32 v[2:3], v[44:45], v[86:87] op_sel_hi:[1,0]
	v_add_u32_e32 v4, 0x1ce0, v79
	s_add_i32 s6, s6, s12
	ds_write2_b32 v4, v2, v3 offset1:1
	v_pk_mul_f32 v[2:3], v[46:47], v[86:87] op_sel_hi:[1,0]
	v_add_u32_e32 v4, 0x1ce8, v79
	s_lshl_b32 s12, s6, 6
	ds_write2_b32 v4, v2, v3 offset1:1
	s_mulk_i32 s6, 0xd400
	s_waitcnt lgkmcnt(0)
	s_add_i32 s6, s6, s7
	ds_read2_b32 v[6:7], v77 offset0:33 offset1:41
	ds_read2_b32 v[12:13], v77 offset1:8
	ds_read2_b32 v[14:15], v77 offset0:66 offset1:74
	ds_read2_b32 v[20:21], v77 offset0:99 offset1:107
	ds_read2_b32 v[22:23], v77 offset0:132 offset1:140
	ds_read2_b32 v[24:25], v77 offset0:165 offset1:173
	ds_read2_b32 v[26:27], v77 offset0:198 offset1:206
	ds_read2_b32 v[28:29], v77 offset0:231 offset1:239
	v_add_u32_e32 v38, s6, v83
	s_waitcnt lgkmcnt(6)
	v_cvt_pk_bf16_f32 v2, v12, v6
	v_add_u32_e32 v6, 0xffffea00, v38
	v_cmp_lt_i32_e32 vcc, s18, v38
	s_waitcnt lgkmcnt(4)
	v_cvt_pk_bf16_f32 v3, v14, v20
	s_ashr_i32 s13, s12, 31
	v_cndmask_b32_e32 v6, v38, v6, vcc
	v_lshlrev_b32_e32 v12, 1, v6
	v_and_b32_e32 v12, 0xffffff00, v12
	v_cndmask_b32_e32 v14, 0, v81, vcc
	v_and_b32_e32 v6, 0x67, v6
	v_or3_b32 v36, v6, v14, v12
	v_ashrrev_i32_e32 v37, 31, v36
	v_lshl_add_u64 v[30:31], s[12:13], 1, v[70:71]
	v_lshlrev_b64 v[36:37], 12, v[36:37]
	s_waitcnt lgkmcnt(2)
	v_cvt_pk_bf16_f32 v4, v22, v24
	s_waitcnt lgkmcnt(0)
	v_cvt_pk_bf16_f32 v5, v26, v28
	v_lshl_add_u64 v[36:37], v[30:31], 0, v[36:37]
	v_add_u32_e32 v6, 8, v38
	global_store_dwordx4 v[36:37], v[2:5], off sc0 sc1
	v_cmp_lt_i32_e32 vcc, s18, v6
	s_waitcnt vmcnt(3)
	v_mov_b64_e32 v[48:49], v[60:61]
	v_cvt_pk_bf16_f32 v2, v13, v7
	v_add_u32_e32 v7, 0xffffea08, v38
	v_cndmask_b32_e32 v6, v6, v7, vcc
	v_lshlrev_b32_e32 v7, 1, v6
	v_and_b32_e32 v7, 0xffffff00, v7
	v_cndmask_b32_e32 v12, 0, v81, vcc
	v_and_b32_e32 v6, 0x6f, v6
	v_or3_b32 v6, v6, v12, v7
	v_ashrrev_i32_e32 v7, 31, v6
	v_lshlrev_b64 v[6:7], 12, v[6:7]
	v_cvt_pk_bf16_f32 v3, v15, v21
	v_cvt_pk_bf16_f32 v4, v23, v25
	v_cvt_pk_bf16_f32 v5, v27, v29
	v_lshl_add_u64 v[6:7], v[30:31], 0, v[6:7]
	ds_read2_b32 v[12:13], v77 offset0:16 offset1:24
	ds_read2_b32 v[14:15], v77 offset0:49 offset1:57
	ds_read2_b32 v[20:21], v77 offset0:82 offset1:90
	ds_read2_b32 v[22:23], v77 offset0:115 offset1:123
	ds_read2_b32 v[24:25], v77 offset0:148 offset1:156
	ds_read2_b32 v[26:27], v77 offset0:181 offset1:189
	ds_read2_b32 v[28:29], v77 offset0:214 offset1:222
	ds_read2_b32 v[36:37], v77 offset0:247 offset1:255
	global_store_dwordx4 v[6:7], v[2:5], off sc0 sc1
	v_add_u32_e32 v6, 16, v38
	v_add_u32_e32 v7, 0xffffea10, v38
	v_cmp_lt_i32_e32 vcc, s18, v6
	s_waitcnt lgkmcnt(6)
	v_cvt_pk_bf16_f32 v2, v12, v14
	s_waitcnt lgkmcnt(4)
	v_cvt_pk_bf16_f32 v3, v20, v22
	v_cndmask_b32_e32 v6, v6, v7, vcc
	v_lshlrev_b32_e32 v7, 1, v6
	v_and_b32_e32 v7, 0xffffff00, v7
	v_cndmask_b32_e32 v12, 0, v81, vcc
	v_and_b32_e32 v6, 0x77, v6
	v_or3_b32 v6, v6, v12, v7
	v_ashrrev_i32_e32 v7, 31, v6
	v_lshlrev_b64 v[6:7], 12, v[6:7]
	s_waitcnt lgkmcnt(2)
	v_cvt_pk_bf16_f32 v4, v24, v26
	s_waitcnt lgkmcnt(0)
	v_cvt_pk_bf16_f32 v5, v28, v36
	v_lshl_add_u64 v[6:7], v[30:31], 0, v[6:7]
	global_store_dwordx4 v[6:7], v[2:5], off sc0 sc1
	s_waitcnt vmcnt(4)
	v_mov_b64_e32 v[44:45], v[64:65]
	v_add_u32_e32 v83, s14, v83
	v_add_u32_e32 v2, 24, v38
	v_add_u32_e32 v3, 0xffffea18, v38
	v_cmp_lt_i32_e32 vcc, s18, v2
	v_cvt_pk_bf16_f32 v5, v29, v37
	v_mov_b64_e32 v[36:37], v[52:53]
	v_cndmask_b32_e32 v2, v2, v3, vcc
	v_lshlrev_b32_e32 v3, 1, v2
	v_and_b32_e32 v3, 0xffffff00, v3
	v_cndmask_b32_e32 v4, 0, v81, vcc
	v_and_b32_e32 v2, 0x7f, v2
	v_or3_b32 v6, v2, v4, v3
	v_ashrrev_i32_e32 v7, 31, v6
	v_lshlrev_b64 v[6:7], 12, v[6:7]
	v_cvt_pk_bf16_f32 v2, v13, v15
	v_cvt_pk_bf16_f32 v3, v21, v23
	v_cvt_pk_bf16_f32 v4, v25, v27
	v_lshl_add_u64 v[6:7], v[30:31], 0, v[6:7]
	global_store_dwordx4 v[6:7], v[2:5], off
	s_waitcnt lgkmcnt(0)
	v_mov_b64_e32 v[12:13], v[16:17]
	v_mov_b64_e32 v[24:25], v[32:33]
	v_mov_b64_e32 v[4:5], v[8:9]
	v_mov_b64_e32 v[20:21], v[40:41]
	v_mov_b64_e32 v[28:29], v[56:57]
	s_add_i32 s19, s19, s14
	v_add_u32_e32 v73, s14, v73
	s_andn2_b64 vcc, exec, s[10:11]
	s_mov_b32 s6, s20
	v_mov_b64_e32 v[14:15], v[18:19]
	v_mov_b64_e32 v[6:7], v[10:11]
	v_mov_b64_e32 v[26:27], v[34:35]
	v_mov_b64_e32 v[22:23], v[42:43]
	v_mov_b64_e32 v[38:39], v[54:55]
	v_mov_b64_e32 v[30:31], v[58:59]
	v_mov_b64_e32 v[50:51], v[62:63]
	v_mov_b64_e32 v[46:47], v[66:67]
	v_mov_b32_e32 v72, v85
	v_mov_b32_e32 v74, v87
	v_mov_b32_e32 v76, v89
	v_mov_b32_e32 v78, v94
	v_mov_b32_e32 v80, v95
	v_mov_b32_e32 v82, v96
	v_mov_b32_e32 v84, v97
	s_waitcnt vmcnt(4)
	v_mov_b32_e32 v86, v1
	s_cbranch_vccz .LBB0_1862

; #define LAS __attribute__((address_space(3)))
; __device__ __forceinline__ unsigned cvtpk(float lo, float hi) { f32x2 v = {lo, hi}; bf16x2_t b = __builtin_convertvector(v, bf16x2_t); return __builtin_bit_cast(unsigned, b); }
; __device__ __forceinline__ void witem_store(const WItem& w, int K, bf16_t* WT, int kvperm, LAS float* scr, int item, int nblk, int lane) {
;     ...
;     for (int i = 0; i < 8; ++i) { LAS float* d = scr + (8 * i + rr) * 33 + col; const float g = w.g[i]; d[0] = w.v[i].x * g; d[1] = w.v[i].y * g; d[2] = w.v[i].z * g; d[3] = w.v[i].w * g; }
;     asm volatile("s_waitcnt lgkmcnt(0)" ::: "memory");
;     const int c = lane & 7;
; #pragma unroll
;     for (int j = 0; j < 4; ++j) { const int n = (lane >> 3) + 8 * j; const LAS float* s = scr + (8 * c) * 33 + n;
;         u32x4 o; o.x = cvtpk(s[0 * 33], s[1 * 33]); o.y = cvtpk(s[2 * 33], s[3 * 33]); o.z = cvtpk(s[4 * 33], s[5 * 33]); o.w = cvtpk(s[6 * 33], s[7 * 33]);
;         int nr = n0 + n; if (kvperm == 1) { const int hh = nr >> 8, ww = nr & 255; nr = (ww < 128) ? hh * 128 + ww : 2048 + hh * 128 + (ww - 128); }
;         else if (kvperm == 2) { const int isv = nr >= 5632, f = isv ? nr - 5632 : nr; nr = (f >> 7) * 256 + isv * 128 + (f & 127); }
;         *(u32x4*)(WT + (size_t)nr * K + k0 + 8 * c) = o; }
;     ...
;     while (it < i1) {
;         cur = nxt;
;         const int nit = it + NGW;
;         if (nit < i1) witem_load(nxt, W, N, gk, nit, nblk, lane);
;         witem_store(cur, K, WT, kvperm, scr, it, nblk, lane);
;         it = nit;
;     }
.LBB0_2334:
	v_pk_mul_f32 v[2:3], v[8:9], v[72:73] op_sel_hi:[1,0]
	ds_write2_b32 v79, v2, v3 offset1:1
	v_pk_mul_f32 v[2:3], v[10:11], v[72:73] op_sel_hi:[1,0]
	ds_write2_b32 v79, v2, v3 offset0:2 offset1:3
	v_pk_mul_f32 v[2:3], v[4:5], v[74:75] op_sel_hi:[1,0]
	v_add_u32_e32 v4, 0x420, v79
	ds_write2_b32 v4, v2, v3 offset1:1
	v_pk_mul_f32 v[2:3], v[6:7], v[74:75] op_sel_hi:[1,0]
	v_add_u32_e32 v4, 0x428, v79
	ds_write2_b32 v4, v2, v3 offset1:1
	v_pk_mul_f32 v[2:3], v[24:25], v[76:77] op_sel_hi:[1,0]
	v_add_u32_e32 v4, 0x840, v79
	ds_write2_b32 v4, v2, v3 offset1:1
	v_pk_mul_f32 v[2:3], v[26:27], v[76:77] op_sel_hi:[1,0]
	v_add_u32_e32 v4, 0x848, v79
	ds_write2_b32 v4, v2, v3 offset1:1
	v_pk_mul_f32 v[2:3], v[20:21], v[78:79] op_sel_hi:[1,0]
	v_add_u32_e32 v4, 0xc60, v79
	ds_write2_b32 v4, v2, v3 offset1:1
	v_pk_mul_f32 v[2:3], v[22:23], v[78:79] op_sel_hi:[1,0]
	v_add_u32_e32 v4, 0xc68, v79
	ds_write2_b32 v4, v2, v3 offset1:1
	v_pk_mul_f32 v[2:3], v[36:37], v[80:81] op_sel_hi:[1,0]
	v_add_u32_e32 v4, 0x1080, v79
	ds_write2_b32 v4, v2, v3 offset1:1
	v_pk_mul_f32 v[2:3], v[38:39], v[80:81] op_sel_hi:[1,0]
	v_add_u32_e32 v4, 0x1088, v79
	ds_write2_b32 v4, v2, v3 offset1:1
	v_pk_mul_f32 v[2:3], v[28:29], v[82:83] op_sel_hi:[1,0]
	v_add_u32_e32 v4, 0x14a0, v79
	ds_write2_b32 v4, v2, v3 offset1:1
	v_pk_mul_f32 v[2:3], v[30:31], v[82:83] op_sel_hi:[1,0]
	v_add_u32_e32 v4, 0x14a8, v79
	ds_write2_b32 v4, v2, v3 offset1:1
	s_waitcnt vmcnt(7)
	v_pk_mul_f32 v[2:3], v[48:49], v[84:85] op_sel_hi:[1,0]
	v_add_u32_e32 v4, 0x18c0, v79
	s_mul_hi_i32 s3, s3, 0x2e8ba2e9
	ds_write2_b32 v4, v2, v3 offset1:1
	v_pk_mul_f32 v[2:3], v[50:51], v[84:85] op_sel_hi:[1,0]
	v_add_u32_e32 v4, 0x18c8, v79
	s_lshr_b32 s8, s3, 31
	s_ashr_i32 s3, s3, 6
	ds_write2_b32 v4, v2, v3 offset1:1
	s_waitcnt vmcnt(6)
	v_pk_mul_f32 v[2:3], v[44:45], v[86:87] op_sel_hi:[1,0]
	v_add_u32_e32 v4, 0x1ce0, v79
	s_add_i32 s3, s3, s8
	ds_write2_b32 v4, v2, v3 offset1:1
	v_pk_mul_f32 v[2:3], v[46:47], v[86:87] op_sel_hi:[1,0]
	v_add_u32_e32 v4, 0x1ce8, v79
	s_lshl_b32 s8, s3, 6
	ds_write2_b32 v4, v2, v3 offset1:1
	s_mulk_i32 s3, 0xd400
	s_waitcnt lgkmcnt(0)
	s_add_i32 s3, s3, s6
	ds_read2_b32 v[6:7], v77 offset0:33 offset1:41
	ds_read2_b32 v[8:9], v77 offset1:8
	ds_read2_b32 v[10:11], v77 offset0:66 offset1:74
	ds_read2_b32 v[20:21], v77 offset0:99 offset1:107
	ds_read2_b32 v[22:23], v77 offset0:132 offset1:140
	ds_read2_b32 v[24:25], v77 offset0:165 offset1:173
	ds_read2_b32 v[26:27], v77 offset0:198 offset1:206
	ds_read2_b32 v[28:29], v77 offset0:231 offset1:239
	v_add_u32_e32 v38, s3, v83
	s_waitcnt lgkmcnt(6)
	v_cvt_pk_bf16_f32 v2, v8, v6
	v_add_u32_e32 v6, 0xffffea00, v38
	v_cmp_lt_i32_e32 vcc, s12, v38
	s_waitcnt lgkmcnt(4)
	v_cvt_pk_bf16_f32 v3, v10, v20
	s_ashr_i32 s9, s8, 31
	v_cndmask_b32_e32 v6, v38, v6, vcc
	v_lshlrev_b32_e32 v8, 1, v6
	v_and_b32_e32 v8, 0xffffff00, v8
	v_cndmask_b32_e32 v10, 0, v81, vcc
	v_and_b32_e32 v6, 0x67, v6
	v_or3_b32 v36, v6, v10, v8
	v_ashrrev_i32_e32 v37, 31, v36
	v_lshl_add_u64 v[30:31], s[8:9], 1, v[70:71]
	v_lshlrev_b64 v[36:37], 12, v[36:37]
	s_waitcnt lgkmcnt(2)
	v_cvt_pk_bf16_f32 v4, v22, v24
	s_waitcnt lgkmcnt(0)
	v_cvt_pk_bf16_f32 v5, v26, v28
	v_lshl_add_u64 v[36:37], v[30:31], 0, v[36:37]
	v_add_u32_e32 v6, 8, v38
	global_store_dwordx4 v[36:37], v[2:5], off sc0 sc1
	v_cmp_lt_i32_e32 vcc, s12, v6
	s_waitcnt vmcnt(3)
	v_mov_b64_e32 v[48:49], v[60:61]
	v_cvt_pk_bf16_f32 v2, v9, v7
	v_add_u32_e32 v7, 0xffffea08, v38
	v_cndmask_b32_e32 v6, v6, v7, vcc
	v_lshlrev_b32_e32 v7, 1, v6
	v_and_b32_e32 v7, 0xffffff00, v7
	v_cndmask_b32_e32 v8, 0, v81, vcc
	v_and_b32_e32 v6, 0x6f, v6
	v_or3_b32 v6, v6, v8, v7
	v_ashrrev_i32_e32 v7, 31, v6
	v_lshlrev_b64 v[6:7], 12, v[6:7]
	v_cvt_pk_bf16_f32 v3, v11, v21
	v_cvt_pk_bf16_f32 v4, v23, v25
	v_cvt_pk_bf16_f32 v5, v27, v29
	v_lshl_add_u64 v[6:7], v[30:31], 0, v[6:7]
	ds_read2_b32 v[8:9], v77 offset0:16 offset1:24
	ds_read2_b32 v[10:11], v77 offset0:49 offset1:57
	ds_read2_b32 v[20:21], v77 offset0:82 offset1:90
	ds_read2_b32 v[22:23], v77 offset0:115 offset1:123
	ds_read2_b32 v[24:25], v77 offset0:148 offset1:156
	ds_read2_b32 v[26:27], v77 offset0:181 offset1:189
	ds_read2_b32 v[28:29], v77 offset0:214 offset1:222
	ds_read2_b32 v[36:37], v77 offset0:247 offset1:255
	global_store_dwordx4 v[6:7], v[2:5], off sc0 sc1
	v_add_u32_e32 v6, 16, v38
	v_add_u32_e32 v7, 0xffffea10, v38
	v_cmp_lt_i32_e32 vcc, s12, v6
	s_waitcnt lgkmcnt(6)
	v_cvt_pk_bf16_f32 v2, v8, v10
	s_waitcnt lgkmcnt(4)
	v_cvt_pk_bf16_f32 v3, v20, v22
	v_cndmask_b32_e32 v6, v6, v7, vcc
	v_lshlrev_b32_e32 v7, 1, v6
	v_and_b32_e32 v7, 0xffffff00, v7
	v_cndmask_b32_e32 v8, 0, v81, vcc
	v_and_b32_e32 v6, 0x77, v6
	v_or3_b32 v6, v6, v8, v7
	v_ashrrev_i32_e32 v7, 31, v6
	v_lshlrev_b64 v[6:7], 12, v[6:7]
	s_waitcnt lgkmcnt(2)
	v_cvt_pk_bf16_f32 v4, v24, v26
	s_waitcnt lgkmcnt(0)
	v_cvt_pk_bf16_f32 v5, v28, v36
	v_lshl_add_u64 v[6:7], v[30:31], 0, v[6:7]
	global_store_dwordx4 v[6:7], v[2:5], off sc0 sc1
	s_waitcnt vmcnt(4)
	v_mov_b64_e32 v[44:45], v[64:65]
	v_add_u32_e32 v83, s7, v83
	v_add_u32_e32 v2, 24, v38
	v_add_u32_e32 v3, 0xffffea18, v38
	v_cmp_lt_i32_e32 vcc, s12, v2
	v_cvt_pk_bf16_f32 v5, v29, v37
	v_mov_b64_e32 v[36:37], v[52:53]
	v_cndmask_b32_e32 v2, v2, v3, vcc
	v_lshlrev_b32_e32 v3, 1, v2
	v_and_b32_e32 v3, 0xffffff00, v3
	v_cndmask_b32_e32 v4, 0, v81, vcc
	v_and_b32_e32 v2, 0x7f, v2
	v_or3_b32 v6, v2, v4, v3
	v_ashrrev_i32_e32 v7, 31, v6
	v_lshlrev_b64 v[6:7], 12, v[6:7]
	v_cvt_pk_bf16_f32 v2, v9, v11
	v_cvt_pk_bf16_f32 v3, v21, v23
	v_cvt_pk_bf16_f32 v4, v25, v27
	v_lshl_add_u64 v[6:7], v[30:31], 0, v[6:7]
	global_store_dwordx4 v[6:7], v[2:5], off
	s_waitcnt lgkmcnt(0)
	v_mov_b64_e32 v[8:9], v[16:17]
	v_mov_b64_e32 v[24:25], v[32:33]
	v_mov_b64_e32 v[4:5], v[12:13]
	v_mov_b64_e32 v[20:21], v[40:41]
	v_mov_b64_e32 v[28:29], v[56:57]
	s_add_i32 s13, s13, s7
	v_add_u32_e32 v73, s7, v73
	s_andn2_b64 vcc, exec, s[4:5]
	s_mov_b32 s3, s14
	v_mov_b64_e32 v[10:11], v[18:19]
	v_mov_b64_e32 v[6:7], v[14:15]
	v_mov_b64_e32 v[26:27], v[34:35]
	v_mov_b64_e32 v[22:23], v[42:43]
	v_mov_b64_e32 v[38:39], v[54:55]
	v_mov_b64_e32 v[30:31], v[58:59]
	v_mov_b64_e32 v[50:51], v[62:63]
	v_mov_b64_e32 v[46:47], v[66:67]
	v_mov_b32_e32 v72, v85
	v_mov_b32_e32 v74, v87
	v_mov_b32_e32 v76, v89
	v_mov_b32_e32 v78, v94
	v_mov_b32_e32 v80, v95
	v_mov_b32_e32 v82, v96
	v_mov_b32_e32 v84, v97
	s_waitcnt vmcnt(4)
	v_mov_b32_e32 v86, v1
	s_cbranch_vccz .LBB0_2352

; #define LAS __attribute__((address_space(3)))
; __device__ __forceinline__ unsigned cvtpk(float lo, float hi) { f32x2 v = {lo, hi}; bf16x2_t b = __builtin_convertvector(v, bf16x2_t); return __builtin_bit_cast(unsigned, b); }
; __device__ __forceinline__ void witem_store(const WItem& w, int K, bf16_t* WT, int kvperm, LAS float* scr, int item, int nblk, int lane) {
;     ...
;     for (int i = 0; i < 8; ++i) { LAS float* d = scr + (8 * i + rr) * 33 + col; const float g = w.g[i]; d[0] = w.v[i].x * g; d[1] = w.v[i].y * g; d[2] = w.v[i].z * g; d[3] = w.v[i].w * g; }
;     asm volatile("s_waitcnt lgkmcnt(0)" ::: "memory");
;     const int c = lane & 7;
; #pragma unroll
;     for (int j = 0; j < 4; ++j) { const int n = (lane >> 3) + 8 * j; const LAS float* s = scr + (8 * c) * 33 + n;
;         u32x4 o; o.x = cvtpk(s[0 * 33], s[1 * 33]); o.y = cvtpk(s[2 * 33], s[3 * 33]); o.z = cvtpk(s[4 * 33], s[5 * 33]); o.w = cvtpk(s[6 * 33], s[7 * 33]);
;         int nr = n0 + n; if (kvperm == 1) { const int hh = nr >> 8, ww = nr & 255; nr = (ww < 128) ? hh * 128 + ww : 2048 + hh * 128 + (ww - 128); }
;         else if (kvperm == 2) { const int isv = nr >= 5632, f = isv ? nr - 5632 : nr; nr = (f >> 7) * 256 + isv * 128 + (f & 127); }
;         *(u32x4*)(WT + (size_t)nr * K + k0 + 8 * c) = o; }
;     ...
;     while (it < i1) {
;         cur = nxt;
;         const int nit = it + NGW;
;         if (nit < i1) witem_load(nxt, W, N, gk, nit, nblk, lane);
;         witem_store(cur, K, WT, kvperm, scr, it, nblk, lane);
;         it = nit;
;     }
.LBB0_2612:
	v_pk_mul_f32 v[2:3], v[16:17], v[72:73] op_sel_hi:[1,0]
	ds_write2_b32 v79, v2, v3 offset1:1
	v_pk_mul_f32 v[2:3], v[18:19], v[72:73] op_sel_hi:[1,0]
	ds_write2_b32 v79, v2, v3 offset0:2 offset1:3
	v_pk_mul_f32 v[2:3], v[4:5], v[74:75] op_sel_hi:[1,0]
	v_add_u32_e32 v4, 0x420, v79
	ds_write2_b32 v4, v2, v3 offset1:1
	v_pk_mul_f32 v[2:3], v[6:7], v[74:75] op_sel_hi:[1,0]
	v_add_u32_e32 v4, 0x428, v79
	ds_write2_b32 v4, v2, v3 offset1:1
	v_pk_mul_f32 v[2:3], v[24:25], v[76:77] op_sel_hi:[1,0]
	v_add_u32_e32 v4, 0x840, v79
	ds_write2_b32 v4, v2, v3 offset1:1
	v_pk_mul_f32 v[2:3], v[26:27], v[76:77] op_sel_hi:[1,0]
	v_add_u32_e32 v4, 0x848, v79
	ds_write2_b32 v4, v2, v3 offset1:1
	v_pk_mul_f32 v[2:3], v[20:21], v[78:79] op_sel_hi:[1,0]
	v_add_u32_e32 v4, 0xc60, v79
	ds_write2_b32 v4, v2, v3 offset1:1
	v_pk_mul_f32 v[2:3], v[22:23], v[78:79] op_sel_hi:[1,0]
	v_add_u32_e32 v4, 0xc68, v79
	ds_write2_b32 v4, v2, v3 offset1:1
	v_pk_mul_f32 v[2:3], v[36:37], v[80:81] op_sel_hi:[1,0]
	v_add_u32_e32 v4, 0x1080, v79
	ds_write2_b32 v4, v2, v3 offset1:1
	v_pk_mul_f32 v[2:3], v[38:39], v[80:81] op_sel_hi:[1,0]
	v_add_u32_e32 v4, 0x1088, v79
	ds_write2_b32 v4, v2, v3 offset1:1
	v_pk_mul_f32 v[2:3], v[32:33], v[82:83] op_sel_hi:[1,0]
	v_add_u32_e32 v4, 0x14a0, v79
	s_mul_hi_i32 s8, s12, 0x2e8ba2e9
	ds_write2_b32 v4, v2, v3 offset1:1
	v_pk_mul_f32 v[2:3], v[34:35], v[82:83] op_sel_hi:[1,0]
	v_add_u32_e32 v4, 0x14a8, v79
	s_lshr_b32 s9, s8, 31
	s_ashr_i32 s8, s8, 6
	ds_write2_b32 v4, v2, v3 offset1:1
	s_waitcnt vmcnt(7)
	v_pk_mul_f32 v[2:3], v[48:49], v[84:85] op_sel_hi:[1,0]
	v_add_u32_e32 v4, 0x18c0, v79
	s_add_i32 s12, s8, s9
	ds_write2_b32 v4, v2, v3 offset1:1
	v_pk_mul_f32 v[2:3], v[50:51], v[84:85] op_sel_hi:[1,0]
	v_add_u32_e32 v4, 0x18c8, v79
	s_lshl_b32 s8, s12, 6
	ds_write2_b32 v4, v2, v3 offset1:1
	s_waitcnt vmcnt(6)
	v_pk_mul_f32 v[2:3], v[44:45], v[86:87] op_sel_hi:[1,0]
	v_add_u32_e32 v4, 0x1ce0, v79
	ds_write2_b32 v4, v2, v3 offset1:1
	v_pk_mul_f32 v[2:3], v[46:47], v[86:87] op_sel_hi:[1,0]
	v_add_u32_e32 v4, 0x1ce8, v79
	s_ashr_i32 s9, s8, 31
	ds_write2_b32 v4, v2, v3 offset1:1
	v_lshl_add_u64 v[34:35], s[8:9], 1, v[70:71]
	s_mul_i32 s8, s12, 0xffffd400
	s_waitcnt lgkmcnt(0)
	s_add_i32 s8, s8, s3
	ds_read2_b32 v[6:7], v75 offset0:33 offset1:41
	ds_read2_b32 v[16:17], v75 offset1:8
	ds_read2_b32 v[18:19], v75 offset0:66 offset1:74
	ds_read2_b32 v[20:21], v75 offset0:99 offset1:107
	ds_read2_b32 v[22:23], v75 offset0:132 offset1:140
	ds_read2_b32 v[24:25], v75 offset0:165 offset1:173
	ds_read2_b32 v[26:27], v75 offset0:198 offset1:206
	ds_read2_b32 v[32:33], v75 offset0:231 offset1:239
	v_add_u32_e32 v38, s8, v83
	s_waitcnt lgkmcnt(6)
	v_cvt_pk_bf16_f32 v2, v16, v6
	v_add_u32_e32 v6, 0xffffea00, v38
	v_cmp_lt_i32_e32 vcc, s11, v38
	s_waitcnt lgkmcnt(4)
	v_cvt_pk_bf16_f32 v3, v18, v20
	s_waitcnt lgkmcnt(2)
	v_cvt_pk_bf16_f32 v4, v22, v24
	v_cndmask_b32_e32 v6, v38, v6, vcc
	v_lshlrev_b32_e32 v16, 1, v6
	v_and_b32_e32 v16, 0xffffff00, v16
	v_cndmask_b32_e32 v18, 0, v81, vcc
	v_and_b32_e32 v6, 0x67, v6
	v_or3_b32 v36, v6, v18, v16
	v_ashrrev_i32_e32 v37, 31, v36
	v_lshlrev_b64 v[36:37], 12, v[36:37]
	s_waitcnt lgkmcnt(0)
	v_cvt_pk_bf16_f32 v5, v26, v32
	v_lshl_add_u64 v[36:37], v[34:35], 0, v[36:37]
	v_add_u32_e32 v6, 8, v38
	global_store_dwordx4 v[36:37], v[2:5], off sc0 sc1
	v_cmp_lt_i32_e32 vcc, s11, v6
	s_waitcnt vmcnt(3)
	v_mov_b64_e32 v[48:49], v[60:61]
	v_cvt_pk_bf16_f32 v2, v17, v7
	v_add_u32_e32 v7, 0xffffea08, v38
	v_cndmask_b32_e32 v6, v6, v7, vcc
	v_lshlrev_b32_e32 v7, 1, v6
	v_and_b32_e32 v7, 0xffffff00, v7
	v_cndmask_b32_e32 v16, 0, v81, vcc
	v_and_b32_e32 v6, 0x6f, v6
	v_or3_b32 v6, v6, v16, v7
	v_ashrrev_i32_e32 v7, 31, v6
	v_lshlrev_b64 v[6:7], 12, v[6:7]
	v_cvt_pk_bf16_f32 v3, v19, v21
	v_cvt_pk_bf16_f32 v4, v23, v25
	v_cvt_pk_bf16_f32 v5, v27, v33
	v_lshl_add_u64 v[6:7], v[34:35], 0, v[6:7]
	ds_read2_b32 v[16:17], v75 offset0:16 offset1:24
	ds_read2_b32 v[18:19], v75 offset0:49 offset1:57
	ds_read2_b32 v[20:21], v75 offset0:82 offset1:90
	ds_read2_b32 v[22:23], v75 offset0:115 offset1:123
	ds_read2_b32 v[24:25], v75 offset0:148 offset1:156
	ds_read2_b32 v[26:27], v75 offset0:181 offset1:189
	ds_read2_b32 v[32:33], v75 offset0:214 offset1:222
	ds_read2_b32 v[36:37], v75 offset0:247 offset1:255
	global_store_dwordx4 v[6:7], v[2:5], off sc0 sc1
	v_add_u32_e32 v6, 16, v38
	v_add_u32_e32 v7, 0xffffea10, v38
	v_cmp_lt_i32_e32 vcc, s11, v6
	s_waitcnt lgkmcnt(6)
	v_cvt_pk_bf16_f32 v2, v16, v18
	s_waitcnt lgkmcnt(4)
	v_cvt_pk_bf16_f32 v3, v20, v22
	v_cndmask_b32_e32 v6, v6, v7, vcc
	v_lshlrev_b32_e32 v7, 1, v6
	v_and_b32_e32 v7, 0xffffff00, v7
	v_cndmask_b32_e32 v16, 0, v81, vcc
	v_and_b32_e32 v6, 0x77, v6
	v_or3_b32 v6, v6, v16, v7
	v_ashrrev_i32_e32 v7, 31, v6
	v_lshlrev_b64 v[6:7], 12, v[6:7]
	s_waitcnt lgkmcnt(2)
	v_cvt_pk_bf16_f32 v4, v24, v26
	s_waitcnt lgkmcnt(0)
	v_cvt_pk_bf16_f32 v5, v32, v36
	v_lshl_add_u64 v[6:7], v[34:35], 0, v[6:7]
	global_store_dwordx4 v[6:7], v[2:5], off sc0 sc1
	s_waitcnt vmcnt(4)
	v_mov_b64_e32 v[44:45], v[64:65]
	v_add_u32_e32 v83, s6, v83
	v_add_u32_e32 v2, 24, v38
	v_add_u32_e32 v3, 0xffffea18, v38
	v_cmp_lt_i32_e32 vcc, s11, v2
	v_cvt_pk_bf16_f32 v5, v33, v37
	v_mov_b64_e32 v[36:37], v[52:53]
	v_cndmask_b32_e32 v2, v2, v3, vcc
	v_lshlrev_b32_e32 v3, 1, v2
	v_and_b32_e32 v3, 0xffffff00, v3
	v_cndmask_b32_e32 v4, 0, v81, vcc
	v_and_b32_e32 v2, 0x7f, v2
	v_or3_b32 v6, v2, v4, v3
	v_ashrrev_i32_e32 v7, 31, v6
	v_lshlrev_b64 v[6:7], 12, v[6:7]
	v_cvt_pk_bf16_f32 v2, v17, v19
	v_cvt_pk_bf16_f32 v3, v21, v23
	v_cvt_pk_bf16_f32 v4, v25, v27
	v_lshl_add_u64 v[6:7], v[34:35], 0, v[6:7]
	global_store_dwordx4 v[6:7], v[2:5], off
	s_waitcnt lgkmcnt(0)
	v_mov_b64_e32 v[18:19], v[14:15]
	v_mov_b64_e32 v[24:25], v[28:29]
	v_mov_b64_e32 v[4:5], v[8:9]
	v_mov_b64_e32 v[20:21], v[40:41]
	v_mov_b64_e32 v[32:33], v[56:57]
	s_add_i32 s13, s13, s6
	v_add_u32_e32 v73, s6, v73
	s_andn2_b64 vcc, exec, s[0:1]
	s_mov_b32 s12, s14
	v_mov_b64_e32 v[16:17], v[12:13]
	v_mov_b64_e32 v[6:7], v[10:11]
	v_mov_b64_e32 v[26:27], v[30:31]
	v_mov_b64_e32 v[22:23], v[42:43]
	v_mov_b64_e32 v[38:39], v[54:55]
	v_mov_b64_e32 v[34:35], v[58:59]
	v_mov_b64_e32 v[50:51], v[62:63]
	v_mov_b64_e32 v[46:47], v[66:67]
	v_mov_b32_e32 v72, v85
	v_mov_b32_e32 v74, v87
	v_mov_b32_e32 v76, v89
	v_mov_b32_e32 v78, v94
	v_mov_b32_e32 v80, v95
	v_mov_b32_e32 v82, v96
	v_mov_b32_e32 v84, v97
	s_waitcnt vmcnt(4)
	v_mov_b32_e32 v86, v1
	s_cbranch_vccz .LBB0_2630
